# LRU unit: libm log1pf expansion (4x ~117 VALU per wave per unit) replaced by compensated v_log_f32 form log2(1+e)*ln2*e/((1+e)-1), f32 throughout
# baseline (speedup 1.0000x reference)
; #define LAS __attribute__((address_space(3)))
; template <int MODE>
; __device__ __forceinline__ void lru_unit(const Args& a, int l, int b, int ch, LAS unsigned char* lds) {
;     int tid_ = threadIdx.x; asm volatile("" : "+v"(tid_));
;     const int tid = tid_, w = __builtin_amdgcn_readfirstlane(tid >> 6), lane = tid & 63, r32 = lane & 31, h = lane >> 5;
;     const int c = w * 64 + lane, t0 = ch * 32;
;     const bf16* proj = (const bf16*)(a.ws + WS_PROJ);
;     LAS unsigned char* xcb = lds + w * 12800;
;     LAS float* au = (LAS float*)(lds + w * 12800 + 4608);
;     const float* cw = a.in[7] + (size_t)l * 4 * LW;
;     const float cw0 = cw[c], cw1 = cw[LW + c], cw2 = cw[2 * LW + c], cw3 = cw[3 * LW + c], cb = a.in[8][l * LW + c];
;     float prm[2][2][3];
; #pragma unroll
;     for (int d = 0; d < 2; ++d)
; #pragma unroll
;         for (int nt = 0; nt < 2; ++nt) { const int cc = (l * 2 + d) * LW + w * 64 + nt * 32 + r32;
;             prm[d][nt][0] = a.in[10][cc]; prm[d][nt][1] = a.in[12][cc]; prm[d][nt][2] = a.in[13][cc]; }
;     const bf16* xp = proj + (size_t)b * SEQ * DIN + c;
;     float xin[35], gl[32];
;     unsigned short xraw[35], graw[32];
; #pragma unroll
;     for (int i = 0; i < 35; ++i) { const int t = t0 - 2 + i, tc = t < 0 ? 0 : (t >= SEQ ? SEQ - 1 : t); xraw[i] = xp[(size_t)tc * DIN]; }
.LBB0_180:
	s_cmpk_gt_i32 s65, 0xff
	s_mov_b64 s[0:1], -1
	s_barrier
	s_cbranch_scc0 .LBB0_182
	s_add_i32 s0, s65, 0xffffff00
	s_lshr_b32 s40, s0, 7
	s_mul_i32 s88, s40, 0x700000
	s_and_b32 s28, s65, 0x7f
	s_lshl_b32 s29, s28, 5
	s_lshl_b64 s[0:1], s[88:89], 1
	s_add_u32 s38, s24, s0
	s_addc_u32 s39, s25, s1
	s_lshl_b32 s0, s40, 21
	s_lshl_b32 s1, s28, 14
	s_or_b32 s88, s0, s1
	s_min_u32 s41, s29, 0xfdf
	s_lshl_b64 s[0:1], s[88:89], 2
	s_add_u32 s44, s72, s0
	s_addc_u32 s45, s73, s1
	s_add_u32 s46, s50, s0
	s_addc_u32 s47, s51, s1
	s_lshl_b32 s0, s40, 17
	s_lshl_b32 s1, s28, 10
	s_or_b32 s88, s0, s1
	s_lshl_b64 s[0:1], s[88:89], 3
	s_add_u32 s42, s74, s0
	s_addc_u32 s43, s75, s1
	v_mov_b32_e32 v66, v226
	s_add_u32 s40, s50, s0
	s_movk_i32 s59, 0xffc0
	v_readfirstlane_b32 s0, v66
	s_mul_i32 s88, s28, 0x1c000
	s_mov_b32 s4, 0x1c000
	v_mov_b32_e32 v0, s0
	v_bfi_b32 v82, s59, v0, v66
	v_ashrrev_i32_e32 v83, 31, v82
	v_lshl_add_u64 v[36:37], v[82:83], 1, s[38:39]
	v_lshl_add_u64 v[4:5], v[36:37], 0, s[88:89]
	s_mul_i32 s88, s41, 0xe00
	v_lshl_add_u64 v[2:3], v[36:37], 0, s[88:89]
	v_add_co_u32_e32 v2, vcc, s4, v2
	v_readlane_b32 s4, v254, 37
	s_nop 0
	v_addc_co_u32_e32 v3, vcc, 0, v3, vcc
	global_load_ushort v0, v[2:3], off
	v_lshlrev_b64 v[2:3], 2, v[82:83]
	v_readlane_b32 s5, v254, 38
	s_movk_i32 s61, 0x1000
	s_movk_i32 s59, 0x2000
	v_lshl_add_u64 v[24:25], s[4:5], 0, v[2:3]
	v_add_co_u32_e32 v26, vcc, s61, v24
	s_movk_i32 s60, 0x3000
	s_nop 0
	v_addc_co_u32_e32 v27, vcc, 0, v25, vcc
	v_add_co_u32_e32 v30, vcc, s61, v4
	s_addc_u32 s41, s51, s1
	s_nop 0
	v_addc_co_u32_e32 v31, vcc, 0, v5, vcc
	v_add_co_u32_e32 v28, vcc, s59, v4
	s_movk_i32 s1, 0x4000
	s_nop 0
	v_addc_co_u32_e32 v29, vcc, 0, v5, vcc
	v_add_co_u32_e32 v32, vcc, s60, v4
	v_and_b32_e32 v164, 31, v66
	s_nop 0
	v_addc_co_u32_e32 v33, vcc, 0, v5, vcc
	v_add_co_u32_e32 v22, vcc, s1, v4
	s_movk_i32 s1, 0x5000
	s_nop 0
	v_addc_co_u32_e32 v23, vcc, 0, v5, vcc
	v_add_co_u32_e32 v10, vcc, s1, v4
	s_movk_i32 s1, 0x6000
	s_nop 0
	v_addc_co_u32_e32 v11, vcc, 0, v5, vcc
	v_add_co_u32_e32 v20, vcc, s1, v4
	s_movk_i32 s1, 0x7000
	s_nop 0
	v_addc_co_u32_e32 v21, vcc, 0, v5, vcc
	v_add_co_u32_e32 v18, vcc, s1, v4
	s_mov_b32 s1, 0x8000
	s_nop 0
	v_addc_co_u32_e32 v19, vcc, 0, v5, vcc
	v_add_co_u32_e32 v12, vcc, s1, v4
	s_mov_b32 s1, 0x9000
	s_nop 0
	v_addc_co_u32_e32 v13, vcc, 0, v5, vcc
	v_add_co_u32_e32 v14, vcc, s1, v4
	s_mov_b32 s1, 0xa000
	s_nop 0
	v_addc_co_u32_e32 v15, vcc, 0, v5, vcc
	v_add_co_u32_e32 v16, vcc, s1, v4
	s_mov_b32 s1, 0xc000
	s_nop 0
	v_addc_co_u32_e32 v17, vcc, 0, v5, vcc
	v_add_co_u32_e32 v6, vcc, s90, v4
	v_readlane_b32 s4, v254, 39
	s_nop 0
	v_addc_co_u32_e32 v7, vcc, 0, v5, vcc
	v_add_co_u32_e32 v8, vcc, s1, v4
	s_and_b32 s1, s0, 0xffffffc0
	s_nop 0
	v_addc_co_u32_e32 v9, vcc, 0, v5, vcc
	s_cmpk_lg_i32 s28, 0x7f
	s_cselect_b64 vcc, -1, 0
	s_add_i32 s28, s29, -2
	s_max_i32 s38, s28, 0
	s_add_i32 s29, s29, -1
	s_mul_i32 s88, s38, 0xe00
	s_max_i32 s38, s29, 0
	v_lshl_add_u64 v[34:35], v[36:37], 0, s[88:89]
	s_mul_i32 s88, s38, 0xe00
	v_lshl_add_u64 v[36:37], v[36:37], 0, s[88:89]
	global_load_ushort v64, v[36:37], off
	global_load_ushort v67, v[32:33], off offset:2048
	global_load_ushort v85, v[30:31], off offset:3072
	global_load_ushort v65, v[34:35], off
	v_or_b32_e32 v30, s4, v164
	v_add_u32_e32 v30, s1, v30
	v_ashrrev_i32_e32 v31, 31, v30
	v_readlane_b32 s4, v252, 16
	v_lshlrev_b64 v[32:33], 2, v[30:31]
	v_readlane_b32 s14, v252, 26
	v_readlane_b32 s15, v252, 27
	s_waitcnt vmcnt(4)
	v_lshlrev_b32_e32 v0, 16, v0
	s_mov_b32 s1, 0xd000
	v_lshl_add_u64 v[68:69], s[14:15], 0, v[32:33]
	global_load_dword v30, v[68:69], off
	global_load_ushort v87, v[4:5], off offset:3584
	v_cndmask_b32_e32 v31, 0, v0, vcc
	v_add_co_u32_e32 v34, vcc, s1, v4
	s_mov_b32 s1, 0xe000
	s_nop 0
	v_addc_co_u32_e32 v35, vcc, 0, v5, vcc
	v_add_co_u32_e32 v36, vcc, s1, v4
	s_mov_b32 s1, 0xf000
	s_nop 0
	v_addc_co_u32_e32 v37, vcc, 0, v5, vcc
	v_add_co_u32_e32 v38, vcc, s1, v4
	s_mov_b32 s1, 0x11000
	s_nop 0
	v_addc_co_u32_e32 v39, vcc, 0, v5, vcc
	v_add_co_u32_e32 v40, vcc, s70, v4
	global_load_dword v84, v[68:69], off offset:128
	global_load_dword v88, v[68:69], off offset:2048
	global_load_dword v86, v[68:69], off offset:2176
	v_addc_co_u32_e32 v41, vcc, 0, v5, vcc
	v_add_co_u32_e32 v42, vcc, s1, v4
	s_mov_b32 s1, 0x12000
	s_nop 0
	v_addc_co_u32_e32 v43, vcc, 0, v5, vcc
	v_add_co_u32_e32 v44, vcc, s1, v4
	s_mov_b32 s1, 0x13000
	s_nop 0
	v_addc_co_u32_e32 v45, vcc, 0, v5, vcc
	v_add_co_u32_e32 v46, vcc, s1, v4
	s_mov_b32 s1, 0x14000
	s_nop 0
	v_addc_co_u32_e32 v47, vcc, 0, v5, vcc
	v_add_co_u32_e32 v48, vcc, s1, v4
	s_mov_b32 s1, 0x15000
	s_nop 0
	v_addc_co_u32_e32 v49, vcc, 0, v5, vcc
	v_add_co_u32_e32 v50, vcc, s1, v4
	s_mov_b32 s1, 0x17000
	s_nop 0
	v_addc_co_u32_e32 v51, vcc, 0, v5, vcc
	v_add_co_u32_e32 v52, vcc, s71, v4
	v_readlane_b32 s6, v252, 18
	s_nop 0
	v_addc_co_u32_e32 v53, vcc, 0, v5, vcc
	v_add_co_u32_e32 v54, vcc, s1, v4
	s_mov_b32 s1, 0x18000
	s_nop 0
	v_addc_co_u32_e32 v55, vcc, 0, v5, vcc
	v_add_co_u32_e32 v56, vcc, s1, v4
	s_mov_b32 s1, 0x19000
	s_nop 0
	v_addc_co_u32_e32 v57, vcc, 0, v5, vcc
	v_add_co_u32_e32 v58, vcc, s1, v4
	s_mov_b32 s1, 0x1b000
	s_nop 0
	v_addc_co_u32_e32 v59, vcc, 0, v5, vcc
	v_add_co_u32_e32 v60, vcc, s1, v4
	s_mov_b32 s1, 0x1a000
	s_nop 0
	v_addc_co_u32_e32 v61, vcc, 0, v5, vcc
	v_add_co_u32_e32 v62, vcc, s1, v4
	s_ashr_i32 s1, s0, 6
	s_mul_i32 s0, s1, 0x3200
	s_add_i32 s0, s0, 0
	v_addc_co_u32_e32 v63, vcc, 0, v5, vcc
	s_waitcnt vmcnt(4)
; #define LAS __attribute__((address_space(3)))
; __device__ __forceinline__ unsigned f2bf(float f) { unsigned u = __builtin_bit_cast(unsigned, f); return (u + 0x7fffu + ((u >> 16) & 1u)) >> 16; }
; template <int MODE>
; __device__ __forceinline__ void lru_unit(const Args& a, int l, int b, int ch, LAS unsigned char* lds) {
;     ...
;         for (int nt = 0; nt < 2; ++nt) { const int cc = (l * 2 + d) * LW + w * 64 + nt * 32 + r32;
;             prm[d][nt][0] = a.in[10][cc]; prm[d][nt][1] = a.in[12][cc]; prm[d][nt][2] = a.in[13][cc]; }
;     const bf16* xp = proj + (size_t)b * SEQ * DIN + c;
;     float xin[35], gl[32];
;     unsigned short xraw[35], graw[32];
; #pragma unroll
;     for (int i = 0; i < 35; ++i) { const int t = t0 - 2 + i, tc = t < 0 ? 0 : (t >= SEQ ? SEQ - 1 : t); xraw[i] = xp[(size_t)tc * DIN]; }
;     if (MODE == 1) {
; #pragma unroll
;         for (int t = 0; t < 32; ++t) graw[t] = xp[(size_t)(t0 + t) * DIN + LW];
;     }
;     asm volatile("" ::: "memory");
; #pragma unroll
;     for (int i = 0; i < 35; ++i) { const int t = t0 - 2 + i; xin[i] = (t >= 0 && t < SEQ) ? bf2f(xraw[i]) : 0.f; }
;     if (MODE == 1) {
; #pragma unroll
;         for (int t = 0; t < 32; ++t) gl[t] = gelu_tanh(bf2f(graw[t]));
;     }
;     float xcr[32], hf[32];
; #pragma unroll
;     for (int t = 0; t < 32; ++t) { const float xc = cw0 * xin[t] + cw1 * xin[t + 1] + cw2 * xin[t + 2] + cw3 * xin[t + 3] + cb; xcr[t] = xc; hf[t] = 0.f;
;         *(LAS bf16*)(xcb + t * 144 + lane * 2) = (bf16)f2bf(xc); }
; #pragma unroll
;     for (int d = 0; d < 2; ++d)
; #pragma unroll
;         for (int nt = 0; nt < 2; ++nt) { prm[d][nt][0] *= -1.4426950408889634f; prm[d][nt][1] *= -1.4426950408889634f;
;             prm[d][nt][2] = -8.f * 1.4426950408889634f * log1pf(__expf(-prm[d][nt][2])); }
	v_mul_f32_e32 v30, 0xbfb8aa3b, v30
	v_exp_f32_e32 v30, v30
	s_cmpk_lt_u32 s28, 0x1000
	s_cselect_b64 vcc, -1, 0
	s_cmpk_lt_u32 s29, 0x1000
	v_lshlrev_b32_e32 v0, 16, v65
	v_lshlrev_b32_e32 v64, 16, v64
	s_cselect_b64 s[38:39], -1, 0
	v_cndmask_b32_e64 v65, 0, v64, s[38:39]
	v_cndmask_b32_e32 v64, 0, v0, vcc
	s_mov_b32 s6, 0x3f2aaaab
	v_readlane_b32 s7, v252, 19
	s_mov_b32 s7, 0x3f317218
	v_readlane_b32 s10, v252, 22
	s_mov_b32 s10, 0x7f800000
	v_readlane_b32 s11, v252, 23
	s_waitcnt vmcnt(2)
	v_mul_f32_e32 v68, 0xbfb8aa3b, v84
	v_exp_f32_e32 v84, v68
	s_mov_b32 s11, 0x33800000
	s_lshl_b32 s28, s1, 1
	s_ashr_i32 s29, s28, 31
	s_lshl_b64 s[28:29], s[28:29], 13
	v_readlane_b32 s1, v254, 40
	s_add_u32 s28, s1, s28
	v_add_f32_e32 v216, 1.0, v30
	v_add_f32_e32 v217, -1.0, v216
	v_log_f32_e32 v218, v216
	v_rcp_f32_e32 v219, v217
	v_cmp_eq_f32_e32 vcc, 0, v217
	v_mul_f32_e32 v218, v218, v30
	v_mul_f32_e32 v218, 0x3f317218, v218
	v_mul_f32_e32 v218, v218, v219
	v_cndmask_b32_e32 v126, v218, v30, vcc
	v_readlane_b32 s1, v254, 41
	v_bfe_u32 v165, v66, 5, 1
	s_addc_u32 s29, s1, s29
	s_waitcnt vmcnt(1)
	v_mul_f32_e32 v30, 0xbfb8aa3b, v88
	v_exp_f32_e32 v163, v30
	v_readlane_b32 s14, v254, 43
	v_readlane_b32 s5, v252, 17
	v_readlane_b32 s8, v252, 20
	v_readlane_b32 s9, v252, 21
	v_readlane_b32 s12, v252, 24
	v_readlane_b32 s13, v252, 25
	v_add_f32_e32 v216, 1.0, v84
	v_add_f32_e32 v217, -1.0, v216
	v_log_f32_e32 v218, v216
	v_rcp_f32_e32 v219, v217
	v_cmp_eq_f32_e32 vcc, 0, v217
	v_mul_f32_e32 v218, v218, v84
	v_mul_f32_e32 v218, 0x3f317218, v218
	v_mul_f32_e32 v218, v218, v219
	v_cndmask_b32_e32 v124, v218, v84, vcc
	global_load_ushort v69, v[28:29], off offset:2560
	s_nop 0
	global_load_ushort v4, v[4:5], off
	s_nop 0
	global_load_dword v28, v[24:25], off
	global_load_dword v29, v[24:25], off offset:2048
	s_nop 0
	global_load_dword v24, v[26:27], off
	global_load_dword v25, v[26:27], off offset:2048
	global_load_ushort v22, v[22:23], off offset:1536
	s_nop 0
	global_load_ushort v20, v[20:21], off offset:512
	s_nop 0
	global_load_ushort v21, v[18:19], off
	s_nop 0
	global_load_ushort v18, v[18:19], off offset:3584
	s_nop 0
	global_load_ushort v19, v[12:13], off offset:3072
	global_load_ushort v23, v[14:15], off offset:2560
	s_nop 0
	global_load_ushort v16, v[16:17], off offset:2048
	s_nop 0
	global_load_ushort v17, v[10:11], off offset:1024
	v_lshlrev_b32_e32 v0, 4, v165
	v_lshl_add_u64 v[10:11], s[28:29], 0, v[0:1]
	v_lshlrev_b32_e32 v0, 7, v164
	v_lshl_add_u64 v[90:91], v[10:11], 0, v[0:1]
	v_add_u32_e32 v10, s14, v82
	v_ashrrev_i32_e32 v11, 31, v10
	v_lshl_add_u64 v[10:11], v[10:11], 2, s[4:5]
	global_load_dword v73, v[10:11], off
	v_lshl_add_u64 v[10:11], s[8:9], 0, v[32:33]
	v_lshl_add_u64 v[12:13], s[12:13], 0, v[32:33]
	global_load_dword v128, v[10:11], off
	global_load_dword v125, v[10:11], off offset:128
	global_load_dword v161, v[10:11], off offset:2048
	global_load_dword v159, v[10:11], off offset:2176
	global_load_dword v129, v[12:13], off
	global_load_dword v127, v[12:13], off offset:128
	global_load_dword v162, v[12:13], off offset:2048
	global_load_dword v160, v[12:13], off offset:2176
	global_load_ushort v0, v[6:7], off offset:1536
	global_load_ushort v30, v[8:9], off offset:1024
	global_load_ushort v33, v[34:35], off offset:512
	s_nop 0
	global_load_ushort v34, v[36:37], off
	global_load_ushort v35, v[36:37], off offset:3584
	s_nop 0
	global_load_ushort v36, v[38:39], off offset:3072
	global_load_ushort v37, v[40:41], off offset:2560
	s_nop 0
	global_load_ushort v38, v[42:43], off offset:2048
	global_load_ushort v39, v[44:45], off offset:1536
	global_load_ushort v40, v[46:47], off offset:1024
	global_load_ushort v41, v[48:49], off offset:512
	s_nop 0
	global_load_ushort v42, v[50:51], off
	global_load_ushort v43, v[50:51], off offset:3584
	global_load_ushort v44, v[52:53], off offset:3072
	global_load_ushort v45, v[54:55], off offset:2560
	global_load_ushort v46, v[56:57], off offset:2048
	global_load_ushort v47, v[58:59], off offset:1536
	global_load_ushort v48, v[60:61], off offset:512
	global_load_ushort v49, v[62:63], off offset:1024
	v_lshlrev_b32_e32 v9, 16, v87
	v_lshlrev_b32_e32 v12, 16, v85
	v_and_b32_e32 v84, 63, v66
	v_lshl_add_u32 v32, v84, 1, s0
	v_add_co_u32_e32 v108, vcc, s60, v90
	v_lshl_add_u64 v[122:123], s[44:45], 0, v[2:3]
	s_nop 0
	v_addc_co_u32_e32 v109, vcc, 0, v91, vcc
	s_mov_b32 s1, 0x11f00000
	v_lshlrev_b64 v[82:83], 3, v[82:83]
	v_readlane_b32 s16, v252, 28
	v_readlane_b32 s17, v252, 29
	v_readlane_b32 s18, v252, 30
	v_readlane_b32 s19, v252, 31
	v_readlane_b32 s15, v254, 44
	s_mov_b64 s[8:9], s[26:27]
	s_waitcnt vmcnt(41)
	v_lshlrev_b32_e32 v13, 16, v69
	s_waitcnt vmcnt(40)
	v_lshlrev_b32_e32 v8, 16, v4
	s_waitcnt vmcnt(38)
	v_pk_mul_f32 v[6:7], v[28:29], v[64:65]
	s_nop 0
	v_add_f32_e32 v4, v6, v7
	s_waitcnt vmcnt(36)
	v_pk_mul_f32 v[10:11], v[24:25], v[8:9]
	v_pk_mov_b32 v[6:7], v[64:65], v[8:9] op_sel:[1,0]
	v_add_f32_e32 v4, v10, v4
	v_add_f32_e32 v4, v11, v4
	v_pk_mul_f32 v[6:7], v[28:29], v[6:7]
	v_pk_mul_f32 v[10:11], v[28:29], v[8:9]
	v_pk_mov_b32 v[8:9], v[8:9], v[12:13] op_sel:[1,0]
	v_add_f32_e32 v6, v6, v7
	v_pk_mul_f32 v[14:15], v[24:25], v[8:9]
	v_add_f32_e32 v10, v10, v11
	v_add_f32_e32 v6, v6, v14
	v_add_f32_e32 v50, v6, v15
	v_pk_mul_f32 v[6:7], v[24:25], v[12:13]
	s_waitcnt vmcnt(35)
	v_lshlrev_b32_e32 v11, 16, v22
	v_add_f32_e32 v6, v10, v6
	v_lshlrev_b32_e32 v10, 16, v67
	v_add_f32_e32 v51, v6, v7
	v_pk_mul_f32 v[6:7], v[28:29], v[8:9]
	v_pk_mul_f32 v[8:9], v[28:29], v[12:13]
	v_pk_mov_b32 v[12:13], v[12:13], v[10:11] op_sel:[1,0]
	v_add_f32_e32 v6, v6, v7
	v_pk_mul_f32 v[14:15], v[24:25], v[12:13]
	v_add_f32_e32 v8, v8, v9
	v_add_f32_e32 v6, v6, v14
	v_add_f32_e32 v22, v6, v15
	v_pk_mul_f32 v[6:7], v[24:25], v[10:11]
	s_waitcnt vmcnt(27)
; #define LAS __attribute__((address_space(3)))
; __device__ __forceinline__ unsigned f2bf(float f) { unsigned u = __builtin_bit_cast(unsigned, f); return (u + 0x7fffu + ((u >> 16) & 1u)) >> 16; }
; template <int MODE>
; __device__ __forceinline__ void lru_unit(const Args& a, int l, int b, int ch, LAS unsigned char* lds) {
;     ...
;     for (int i = 0; i < 35; ++i) { const int t = t0 - 2 + i; xin[i] = (t >= 0 && t < SEQ) ? bf2f(xraw[i]) : 0.f; }
;     if (MODE == 1) {
; #pragma unroll
;         for (int t = 0; t < 32; ++t) gl[t] = gelu_tanh(bf2f(graw[t]));
;     }
;     float xcr[32], hf[32];
; #pragma unroll
;     for (int t = 0; t < 32; ++t) { const float xc = cw0 * xin[t] + cw1 * xin[t + 1] + cw2 * xin[t + 2] + cw3 * xin[t + 3] + cb; xcr[t] = xc; hf[t] = 0.f;
;         *(LAS bf16*)(xcb + t * 144 + lane * 2) = (bf16)f2bf(xc); }
	v_add_f32_e32 v85, v73, v4
	v_add_f32_e32 v6, v8, v6
	v_add_f32_e32 v52, v6, v7
	v_pk_mul_f32 v[6:7], v[28:29], v[12:13]
	v_lshlrev_b32_e32 v13, 16, v20
	v_lshlrev_b32_e32 v12, 16, v17
	v_pk_mul_f32 v[8:9], v[28:29], v[10:11]
	v_pk_mov_b32 v[10:11], v[10:11], v[12:13] op_sel:[1,0]
	v_add_f32_e32 v6, v6, v7
	v_pk_mul_f32 v[14:15], v[24:25], v[10:11]
	v_add_f32_e32 v8, v8, v9
	v_add_f32_e32 v6, v6, v14
	v_add_f32_e32 v17, v6, v15
	v_pk_mul_f32 v[6:7], v[24:25], v[12:13]
	v_add_f32_e32 v130, v73, v51
	v_add_f32_e32 v6, v8, v6
	v_add_f32_e32 v20, v6, v7
	v_pk_mul_f32 v[6:7], v[28:29], v[10:11]
	v_lshlrev_b32_e32 v11, 16, v18
	v_lshlrev_b32_e32 v10, 16, v21
	v_pk_mul_f32 v[8:9], v[28:29], v[12:13]
	v_pk_mov_b32 v[12:13], v[12:13], v[10:11] op_sel:[1,0]
	v_add_f32_e32 v6, v6, v7
	v_pk_mul_f32 v[14:15], v[24:25], v[12:13]
	v_add_f32_e32 v8, v8, v9
	v_add_f32_e32 v6, v6, v14
	v_add_f32_e32 v18, v6, v15
	v_pk_mul_f32 v[6:7], v[24:25], v[10:11]
	v_add_f32_e32 v131, v73, v22
	v_add_f32_e32 v6, v8, v6
	v_add_f32_e32 v21, v6, v7
	v_pk_mul_f32 v[6:7], v[28:29], v[12:13]
	v_lshlrev_b32_e32 v13, 16, v23
	v_lshlrev_b32_e32 v12, 16, v19
	v_pk_mul_f32 v[8:9], v[28:29], v[10:11]
	v_pk_mov_b32 v[10:11], v[10:11], v[12:13] op_sel:[1,0]
	v_add_f32_e32 v6, v6, v7
	v_pk_mul_f32 v[14:15], v[24:25], v[10:11]
	v_add_f32_e32 v8, v8, v9
	v_add_f32_e32 v6, v6, v14
	v_add_f32_e32 v19, v6, v15
	v_pk_mul_f32 v[6:7], v[24:25], v[12:13]
	v_add_f32_e32 v132, v73, v52
	v_add_f32_e32 v6, v8, v6
	v_add_f32_e32 v23, v6, v7
	v_pk_mul_f32 v[6:7], v[28:29], v[10:11]
	s_waitcnt vmcnt(18)
	v_lshlrev_b32_e32 v11, 16, v0
	v_lshlrev_b32_e32 v10, 16, v16
	v_pk_mul_f32 v[8:9], v[28:29], v[12:13]
	v_pk_mov_b32 v[12:13], v[12:13], v[10:11] op_sel:[1,0]
	v_add_f32_e32 v0, v6, v7
	v_pk_mul_f32 v[14:15], v[24:25], v[12:13]
	v_pk_mul_f32 v[6:7], v[24:25], v[10:11]
	v_add_f32_e32 v0, v0, v14
	v_add_f32_e32 v16, v0, v15
	v_add_f32_e32 v0, v8, v9
	v_add_f32_e32 v0, v0, v6
	v_add_f32_e32 v53, v0, v7
	v_pk_mul_f32 v[6:7], v[28:29], v[12:13]
	s_waitcnt vmcnt(16)
	v_lshlrev_b32_e32 v13, 16, v33
	v_lshlrev_b32_e32 v12, 16, v30
	v_pk_mul_f32 v[8:9], v[28:29], v[10:11]
	v_pk_mov_b32 v[10:11], v[10:11], v[12:13] op_sel:[1,0]
	v_add_f32_e32 v0, v6, v7
	v_pk_mul_f32 v[14:15], v[24:25], v[10:11]
	v_pk_mul_f32 v[6:7], v[24:25], v[12:13]
	v_add_f32_e32 v0, v0, v14
	v_add_f32_e32 v33, v0, v15
	v_add_f32_e32 v0, v8, v9
	v_add_f32_e32 v0, v0, v6
	v_add_f32_e32 v54, v0, v7
	v_pk_mul_f32 v[6:7], v[28:29], v[10:11]
	s_waitcnt vmcnt(14)
	v_lshlrev_b32_e32 v11, 16, v35
	v_lshlrev_b32_e32 v10, 16, v34
	v_pk_mul_f32 v[8:9], v[28:29], v[12:13]
	v_pk_mov_b32 v[12:13], v[12:13], v[10:11] op_sel:[1,0]
	v_add_f32_e32 v0, v6, v7
	v_pk_mul_f32 v[14:15], v[24:25], v[12:13]
	v_pk_mul_f32 v[6:7], v[24:25], v[10:11]
	v_add_f32_e32 v0, v0, v14
	v_add_f32_e32 v34, v0, v15
	v_add_f32_e32 v0, v8, v9
	v_add_f32_e32 v0, v0, v6
	v_add_f32_e32 v35, v0, v7
	v_pk_mul_f32 v[6:7], v[28:29], v[12:13]
	s_waitcnt vmcnt(12)
	v_lshlrev_b32_e32 v13, 16, v37
	v_lshlrev_b32_e32 v12, 16, v36
	v_pk_mul_f32 v[8:9], v[28:29], v[10:11]
	v_pk_mov_b32 v[10:11], v[10:11], v[12:13] op_sel:[1,0]
	v_add_f32_e32 v0, v6, v7
	v_pk_mul_f32 v[14:15], v[24:25], v[10:11]
	v_pk_mul_f32 v[6:7], v[24:25], v[12:13]
	v_add_f32_e32 v0, v0, v14
	v_add_f32_e32 v36, v0, v15
	v_add_f32_e32 v0, v8, v9
	v_add_f32_e32 v0, v0, v6
	v_add_f32_e32 v37, v0, v7
	v_pk_mul_f32 v[6:7], v[28:29], v[10:11]
	s_waitcnt vmcnt(10)
	v_lshlrev_b32_e32 v11, 16, v39
	v_lshlrev_b32_e32 v10, 16, v38
	v_pk_mul_f32 v[8:9], v[28:29], v[12:13]
	v_pk_mov_b32 v[12:13], v[12:13], v[10:11] op_sel:[1,0]
	v_add_f32_e32 v0, v6, v7
	v_pk_mul_f32 v[14:15], v[24:25], v[12:13]
	v_pk_mul_f32 v[6:7], v[24:25], v[10:11]
	v_add_f32_e32 v0, v0, v14
	v_add_f32_e32 v38, v0, v15
	v_add_f32_e32 v0, v8, v9
	v_add_f32_e32 v0, v0, v6
	v_add_f32_e32 v39, v0, v7
	v_pk_mul_f32 v[6:7], v[28:29], v[12:13]
	s_waitcnt vmcnt(8)
	v_lshlrev_b32_e32 v13, 16, v41
	v_lshlrev_b32_e32 v12, 16, v40
	v_pk_mul_f32 v[8:9], v[28:29], v[10:11]
	v_pk_mov_b32 v[10:11], v[10:11], v[12:13] op_sel:[1,0]
	v_add_f32_e32 v0, v6, v7
	v_pk_mul_f32 v[14:15], v[24:25], v[10:11]
	v_pk_mul_f32 v[6:7], v[24:25], v[12:13]
	v_add_f32_e32 v0, v0, v14
	v_add_f32_e32 v40, v0, v15
	v_add_f32_e32 v0, v8, v9
	v_add_f32_e32 v0, v0, v6
	v_add_f32_e32 v41, v0, v7
	v_pk_mul_f32 v[6:7], v[28:29], v[10:11]
	s_waitcnt vmcnt(6)
	v_lshlrev_b32_e32 v11, 16, v43
	v_lshlrev_b32_e32 v10, 16, v42
	v_pk_mul_f32 v[8:9], v[28:29], v[12:13]
	v_pk_mov_b32 v[12:13], v[12:13], v[10:11] op_sel:[1,0]
	v_add_f32_e32 v0, v6, v7
	v_pk_mul_f32 v[14:15], v[24:25], v[12:13]
	v_pk_mul_f32 v[6:7], v[24:25], v[10:11]
	v_add_f32_e32 v0, v0, v14
	v_add_f32_e32 v42, v0, v15
	v_add_f32_e32 v0, v8, v9
	v_add_f32_e32 v0, v0, v6
	v_add_f32_e32 v43, v0, v7
	v_pk_mul_f32 v[6:7], v[28:29], v[12:13]
	s_waitcnt vmcnt(4)
	v_lshlrev_b32_e32 v13, 16, v45
	v_lshlrev_b32_e32 v12, 16, v44
	v_pk_mul_f32 v[8:9], v[28:29], v[10:11]
	v_pk_mov_b32 v[10:11], v[10:11], v[12:13] op_sel:[1,0]
	v_add_f32_e32 v0, v6, v7
	v_pk_mul_f32 v[14:15], v[24:25], v[10:11]
	v_pk_mul_f32 v[6:7], v[24:25], v[12:13]
	v_add_f32_e32 v0, v0, v14
	v_add_f32_e32 v44, v0, v15
	v_add_f32_e32 v0, v8, v9
	v_add_f32_e32 v0, v0, v6
	v_add_f32_e32 v45, v0, v7
	v_pk_mul_f32 v[6:7], v[28:29], v[10:11]
	s_waitcnt vmcnt(2)
	v_lshlrev_b32_e32 v11, 16, v47
	v_lshlrev_b32_e32 v10, 16, v46
	v_pk_mul_f32 v[8:9], v[28:29], v[12:13]
	v_pk_mov_b32 v[12:13], v[12:13], v[10:11] op_sel:[1,0]
	v_add_f32_e32 v0, v6, v7
	v_pk_mul_f32 v[14:15], v[24:25], v[12:13]
	v_pk_mul_f32 v[6:7], v[24:25], v[10:11]
	v_add_f32_e32 v0, v0, v14
	v_add_f32_e32 v46, v0, v15
	v_add_f32_e32 v0, v8, v9
	v_add_f32_e32 v0, v0, v6
	v_add_f32_e32 v47, v0, v7
	v_pk_mul_f32 v[6:7], v[28:29], v[12:13]
	s_waitcnt vmcnt(0)
; #define LAS __attribute__((address_space(3)))
; #define MFMA32(a, b, c) __builtin_amdgcn_mfma_f32_32x32x16_bf16((a), (b), (c), 0, 0, 0)
; __device__ __forceinline__ unsigned f2bf(float f) { unsigned u = __builtin_bit_cast(unsigned, f); return (u + 0x7fffu + ((u >> 16) & 1u)) >> 16; }
; #define LDS_WAVE_SYNC() asm volatile("s_waitcnt lgkmcnt(0)" ::: "memory")
; template <int DIR, int MODE> ...
;     ...
;         const bf16* wr_ = wl + (size_t)((DIR * 8 + w) * 2) * 4096 + (nt * 32 + r32) * 64 + 8 * h;
; #pragma unroll
;         for (int ks = 0; ks < 4; ++ks) {
;             const bf16x8 bR = *(const bf16x8*)(wr_ + 16 * ks), bI = *(const bf16x8*)(wr_ + 4096 + 16 * ks);
;             accR[nt] = MFMA32(af[ks], bR, accR[nt]); accI[nt] = MFMA32(af[ks], bI, accI[nt]); }
; template <int MODE>
; __device__ __forceinline__ void lru_unit(const Args& a, int l, int b, int ch, LAS unsigned char* lds) {
;     ...
;     for (int t = 0; t < 32; ++t) { const float xc = cw0 * xin[t] + cw1 * xin[t + 1] + cw2 * xin[t + 2] + cw3 * xin[t + 3] + cb; xcr[t] = xc; hf[t] = 0.f;
;         *(LAS bf16*)(xcb + t * 144 + lane * 2) = (bf16)f2bf(xc); }
; #pragma unroll
;     for (int d = 0; d < 2; ++d)
; #pragma unroll
;         for (int nt = 0; nt < 2; ++nt) { prm[d][nt][0] *= -1.4426950408889634f; prm[d][nt][1] *= -1.4426950408889634f;
;             prm[d][nt][2] = -8.f * 1.4426950408889634f * log1pf(__expf(-prm[d][nt][2])); }
;     LDS_WAVE_SYNC();
;     bf16x8 af[4];
; #pragma unroll
;     for (int ks = 0; ks < 4; ++ks) af[ks] = *(const LAS bf16x8*)(xcb + r32 * 144 + (16 * ks + 8 * h) * 2);
	v_lshlrev_b32_e32 v12, 16, v49
	v_lshlrev_b32_e32 v13, 16, v48
	v_pk_mul_f32 v[8:9], v[28:29], v[10:11]
	v_pk_mov_b32 v[10:11], v[10:11], v[12:13] op_sel:[1,0]
	v_add_f32_e32 v0, v6, v7
	v_pk_mul_f32 v[14:15], v[24:25], v[10:11]
	v_pk_mul_f32 v[6:7], v[24:25], v[12:13]
	v_add_f32_e32 v0, v0, v14
	v_add_f32_e32 v14, v0, v15
	v_add_f32_e32 v0, v8, v9
	v_add_f32_e32 v0, v0, v6
	v_add_f32_e32 v12, v0, v7
	v_pk_mul_f32 v[6:7], v[28:29], v[10:11]
	v_mov_b32_e32 v30, v13
	v_pk_mul_f32 v[8:9], v[24:25], v[30:31]
	v_add_f32_e32 v0, v6, v7
	v_add_f32_e32 v0, v0, v8
	v_add_f32_e32 v0, v0, v9
	v_add_f32_e32 v87, v73, v0
	v_bfe_u32 v0, v87, 16, 1
	v_add3_u32 v0, v87, v0, s91
	ds_write_b16_d16_hi v32, v0 offset:4464
	v_bfe_u32 v0, v85, 16, 1
	v_add3_u32 v0, v85, v0, s91
	ds_write_b16_d16_hi v32, v0
	v_add_f32_e32 v0, v73, v50
	v_bfe_u32 v4, v0, 16, 1
	v_add3_u32 v4, v0, v4, s91
	ds_write_b16_d16_hi v32, v4 offset:144
	v_bfe_u32 v4, v130, 16, 1
	v_add3_u32 v4, v130, v4, s91
	ds_write_b16_d16_hi v32, v4 offset:288
	v_bfe_u32 v4, v131, 16, 1
	v_add3_u32 v4, v131, v4, s91
	ds_write_b16_d16_hi v32, v4 offset:432
	v_bfe_u32 v4, v132, 16, 1
	v_add3_u32 v4, v132, v4, s91
	v_add_f32_e32 v133, v73, v17
	ds_write_b16_d16_hi v32, v4 offset:576
	v_bfe_u32 v4, v133, 16, 1
	v_add3_u32 v4, v133, v4, s91
	v_add_f32_e32 v134, v73, v20
	ds_write_b16_d16_hi v32, v4 offset:720
	v_bfe_u32 v4, v134, 16, 1
	v_add3_u32 v4, v134, v4, s91
	v_add_f32_e32 v135, v73, v18
	ds_write_b16_d16_hi v32, v4 offset:864
	v_bfe_u32 v4, v135, 16, 1
	v_add3_u32 v4, v135, v4, s91
	v_add_f32_e32 v136, v73, v21
	ds_write_b16_d16_hi v32, v4 offset:1008
	v_bfe_u32 v4, v136, 16, 1
	v_add3_u32 v4, v136, v4, s91
	v_add_f32_e32 v137, v73, v19
	ds_write_b16_d16_hi v32, v4 offset:1152
	v_bfe_u32 v4, v137, 16, 1
	v_add3_u32 v4, v137, v4, s91
	v_add_f32_e32 v138, v73, v23
	ds_write_b16_d16_hi v32, v4 offset:1296
	v_bfe_u32 v4, v138, 16, 1
	v_add3_u32 v4, v138, v4, s91
	v_add_f32_e32 v139, v73, v16
	ds_write_b16_d16_hi v32, v4 offset:1440
	v_bfe_u32 v4, v139, 16, 1
	v_add3_u32 v4, v139, v4, s91
	v_add_f32_e32 v140, v73, v53
	ds_write_b16_d16_hi v32, v4 offset:1584
	v_bfe_u32 v4, v140, 16, 1
	v_add3_u32 v4, v140, v4, s91
	v_add_f32_e32 v141, v73, v33
	ds_write_b16_d16_hi v32, v4 offset:1728
	v_bfe_u32 v4, v141, 16, 1
	v_add3_u32 v4, v141, v4, s91
	v_add_f32_e32 v142, v73, v54
	ds_write_b16_d16_hi v32, v4 offset:1872
	v_bfe_u32 v4, v142, 16, 1
	v_add3_u32 v4, v142, v4, s91
	v_add_f32_e32 v143, v73, v34
	ds_write_b16_d16_hi v32, v4 offset:2016
	v_bfe_u32 v4, v143, 16, 1
	v_add3_u32 v4, v143, v4, s91
	v_add_f32_e32 v144, v73, v35
	ds_write_b16_d16_hi v32, v4 offset:2160
	v_bfe_u32 v4, v144, 16, 1
	v_add3_u32 v4, v144, v4, s91
	v_add_f32_e32 v145, v73, v36
	ds_write_b16_d16_hi v32, v4 offset:2304
	v_bfe_u32 v4, v145, 16, 1
	v_add3_u32 v4, v145, v4, s91
	v_add_f32_e32 v146, v73, v37
	ds_write_b16_d16_hi v32, v4 offset:2448
	v_bfe_u32 v4, v146, 16, 1
	v_add3_u32 v4, v146, v4, s91
	v_add_f32_e32 v147, v73, v38
	ds_write_b16_d16_hi v32, v4 offset:2592
	v_bfe_u32 v4, v147, 16, 1
	v_add3_u32 v4, v147, v4, s91
	v_add_f32_e32 v148, v73, v39
	ds_write_b16_d16_hi v32, v4 offset:2736
	v_bfe_u32 v4, v148, 16, 1
	v_add3_u32 v4, v148, v4, s91
	v_add_f32_e32 v149, v73, v40
	ds_write_b16_d16_hi v32, v4 offset:2880
	v_bfe_u32 v4, v149, 16, 1
	v_add3_u32 v4, v149, v4, s91
	v_add_f32_e32 v150, v73, v41
	ds_write_b16_d16_hi v32, v4 offset:3024
	v_bfe_u32 v4, v150, 16, 1
	v_add3_u32 v4, v150, v4, s91
	v_add_f32_e32 v151, v73, v42
	ds_write_b16_d16_hi v32, v4 offset:3168
	v_bfe_u32 v4, v151, 16, 1
	v_add3_u32 v4, v151, v4, s91
	v_add_f32_e32 v152, v73, v43
	ds_write_b16_d16_hi v32, v4 offset:3312
	v_bfe_u32 v4, v152, 16, 1
	v_add3_u32 v4, v152, v4, s91
	v_add_f32_e32 v153, v73, v44
	ds_write_b16_d16_hi v32, v4 offset:3456
	v_bfe_u32 v4, v153, 16, 1
	v_add3_u32 v4, v153, v4, s91
	v_add_f32_e32 v154, v73, v45
	ds_write_b16_d16_hi v32, v4 offset:3600
	v_bfe_u32 v4, v154, 16, 1
	v_add3_u32 v4, v154, v4, s91
	v_add_f32_e32 v155, v73, v46
	ds_write_b16_d16_hi v32, v4 offset:3744
	v_bfe_u32 v4, v155, 16, 1
	v_add3_u32 v4, v155, v4, s91
	v_add_f32_e32 v156, v73, v47
	ds_write_b16_d16_hi v32, v4 offset:3888
	v_bfe_u32 v4, v156, 16, 1
	v_add3_u32 v4, v156, v4, s91
	v_add_f32_e32 v157, v73, v14
	ds_write_b16_d16_hi v32, v4 offset:4032
	v_bfe_u32 v4, v157, 16, 1
	v_add3_u32 v4, v157, v4, s91
	v_add_f32_e32 v158, v73, v12
	ds_write_b16_d16_hi v32, v4 offset:4176
	v_bfe_u32 v4, v158, 16, 1
	v_add3_u32 v4, v158, v4, s91
	ds_write_b16_d16_hi v32, v4 offset:4320
	s_waitcnt lgkmcnt(0)
	global_load_dwordx4 v[6:9], v[90:91], off
	global_load_dwordx4 v[10:13], v[108:109], off offset:-4096
	v_add_co_u32_e32 v34, vcc, s59, v90
	s_nop 1
	v_addc_co_u32_e32 v35, vcc, 0, v91, vcc
	global_load_dwordx4 v[14:17], v[90:91], off offset:32
	global_load_dwordx4 v[18:21], v[34:35], off offset:32
	global_load_dwordx4 v[22:25], v[90:91], off offset:64
	global_load_dwordx4 v[26:29], v[34:35], off offset:64
	global_load_dwordx4 v[30:33], v[90:91], off offset:96
	global_load_dwordx4 v[104:107], v[34:35], off offset:96
	v_add_co_u32_e32 v74, vcc, s61, v90
	s_nop 0
	s_nop 0
	v_addc_co_u32_e32 v75, vcc, 0, v91, vcc
	global_load_dwordx4 v[166:169], v[74:75], off
	global_load_dwordx4 v[174:177], v[74:75], off offset:32
	global_load_dwordx4 v[182:185], v[74:75], off offset:64
	v_lshrrev_b32_e32 v5, 1, v66
	v_mul_u32_u24_e32 v4, 0x90, v164
	v_and_b32_e32 v5, 16, v5
	v_add3_u32 v110, s0, v4, v5
	ds_read_b128 v[70:73], v110
	ds_read_b128 v[66:69], v110 offset:32
	global_load_dwordx4 v[170:173], v[74:75], off offset:96
	s_waitcnt vmcnt(11) lgkmcnt(1)
; #define MFMA32(a, b, c) __builtin_amdgcn_mfma_f32_32x32x16_bf16((a), (b), (c), 0, 0, 0)
; template <int DIR, int MODE> ...
;     ...
;         const bf16* wr_ = wl + (size_t)((DIR * 8 + w) * 2) * 4096 + (nt * 32 + r32) * 64 + 8 * h;
; #pragma unroll
;         for (int ks = 0; ks < 4; ++ks) {
;             const bf16x8 bR = *(const bf16x8*)(wr_ + 16 * ks), bI = *(const bf16x8*)(wr_ + 4096 + 16 * ks);
;             accR[nt] = MFMA32(af[ks], bR, accR[nt]); accI[nt] = MFMA32(af[ks], bI, accI[nt]); }
;     }
; #pragma unroll
;     for (int nt = 0; nt < 2; ++nt) {
;         const float nba = prm[DIR][nt][0], nbx = prm[DIR][nt][1], k8l = prm[DIR][nt][2];
; #pragma unroll
;         for (int i = 0; i < 16; ++i) {
;             const float d1 = 1.f + __builtin_amdgcn_exp2f(__builtin_fmaf(accR[nt][i], -1.4426950408889634f, nba));
;             const float d2 = 1.f + __builtin_amdgcn_exp2f(__builtin_fmaf(accI[nt][i], -1.4426950408889634f, nbx));
;             const float inv = __builtin_amdgcn_rcpf(d1 * d2), rr = inv * d2, ii = inv * d1;
;             const float av = __builtin_amdgcn_exp2f(k8l * rr);
;             accR[nt][i] = av; accI[nt][i] = __builtin_amdgcn_sqrtf(fmaxf(__builtin_fmaf(-av, av, 1.f), 0.f)) * ii; }
	v_mfma_f32_32x32x16_bf16 v[34:49], v[70:73], v[6:9], 0
	global_load_dwordx4 v[4:7], v[108:109], off
	global_load_dwordx4 v[178:181], v[108:109], off offset:32
	s_waitcnt vmcnt(12)
	v_mfma_f32_32x32x16_bf16 v[50:65], v[70:73], v[10:13], 0
	ds_read_b128 v[74:77], v110 offset:96
	ds_read_b128 v[78:81], v110 offset:64
	s_waitcnt vmcnt(11) lgkmcnt(2)
	v_mfma_f32_32x32x16_bf16 v[34:49], v[66:69], v[14:17], v[34:49]
	v_mul_f32_e32 v97, 0xbfb8aa3b, v128
	global_load_dwordx4 v[186:189], v[108:109], off offset:64
	global_load_dwordx4 v[200:203], v[108:109], off offset:96
	s_waitcnt vmcnt(12)
	v_mfma_f32_32x32x16_bf16 v[50:65], v[66:69], v[18:21], v[50:65]
	v_mul_f32_e32 v99, 0xbfb8aa3b, v129
	v_mul_f32_e32 v93, 0xbfb8aa3b, v127
	v_lshl_add_u64 v[88:89], s[46:47], 0, v[2:3]
	v_mul_f32_e32 v95, 0xbfb8aa3b, v125
	v_add_co_u32_e32 v120, vcc, s1, v88
	s_waitcnt vmcnt(11) lgkmcnt(0)
	v_mfma_f32_32x32x16_bf16 v[34:49], v[78:81], v[22:25], v[34:49]
	v_addc_co_u32_e32 v121, vcc, 0, v89, vcc
	s_mov_b32 s1, 0x11f01000
	v_add_co_u32_e32 v118, vcc, s1, v88
	s_mov_b32 s1, 0x11f02000
	s_nop 0
	v_addc_co_u32_e32 v119, vcc, 0, v89, vcc
	s_waitcnt vmcnt(10)
	v_mfma_f32_32x32x16_bf16 v[50:65], v[78:81], v[26:29], v[50:65]
	v_add_co_u32_e32 v116, vcc, s1, v88
	s_mov_b32 s1, 0x11f03000
	s_nop 0
	v_addc_co_u32_e32 v117, vcc, 0, v89, vcc
	v_add_co_u32_e32 v114, vcc, s1, v88
	s_waitcnt vmcnt(9)
	v_mfma_f32_32x32x16_bf16 v[34:49], v[74:77], v[30:33], v[34:49]
	v_addc_co_u32_e32 v115, vcc, 0, v89, vcc
	s_mov_b32 s1, 0x11f04000
	v_add_co_u32_e32 v112, vcc, s1, v88
	s_mov_b32 s1, 0x11f05000
	s_nop 0
	v_addc_co_u32_e32 v113, vcc, 0, v89, vcc
	s_waitcnt vmcnt(8)
	v_mfma_f32_32x32x16_bf16 v[50:65], v[74:77], v[104:107], v[50:65]
	s_nop 3
	v_fmamk_f32 v34, v34, 0xbfb8aa3b, v97
	v_fmamk_f32 v101, v35, 0xbfb8aa3b, v97
	v_exp_f32_e32 v34, v34
	v_fmamk_f32 v129, v36, 0xbfb8aa3b, v97
	v_fmamk_f32 v38, v38, 0xbfb8aa3b, v97
	v_fmamk_f32 v39, v39, 0xbfb8aa3b, v97
	v_fmamk_f32 v40, v40, 0xbfb8aa3b, v97
	s_nop 0
	v_fmamk_f32 v50, v50, 0xbfb8aa3b, v99
	v_exp_f32_e32 v35, v50
	v_fmamk_f32 v51, v51, 0xbfb8aa3b, v99
	s_waitcnt vmcnt(7)
	v_mfma_f32_32x32x16_bf16 v[18:33], v[70:73], v[166:169], 0
	v_fmamk_f32 v166, v37, 0xbfb8aa3b, v97
	v_add_f32_e64 v34, v34, 1.0
	v_add_f32_e64 v35, v35, 1.0
	v_exp_f32_e32 v37, v51
	v_mul_f32_e32 v36, v34, v35
	v_rcp_f32_e32 v193, v36
	v_exp_f32_e32 v36, v101
	v_mov_b32_e32 v127, v35
	v_fmamk_f32 v41, v41, 0xbfb8aa3b, v97
	v_fmamk_f32 v42, v42, 0xbfb8aa3b, v97
	v_fmamk_f32 v43, v43, 0xbfb8aa3b, v97
	v_fmamk_f32 v44, v44, 0xbfb8aa3b, v97
	v_fmamk_f32 v45, v45, 0xbfb8aa3b, v97
	v_fmamk_f32 v46, v46, 0xbfb8aa3b, v97
	v_fmamk_f32 v167, v47, 0xbfb8aa3b, v97
	v_fmamk_f32 v168, v48, 0xbfb8aa3b, v97
	v_fmac_f32_e32 v97, 0xbfb8aa3b, v49
	v_pk_mul_f32 v[48:49], v[126:127], v[192:193]
	v_pk_add_f32 v[36:37], v[36:37], 1.0 op_sel_hi:[1,0]
	v_mul_f32_e32 v35, v48, v49
	v_exp_f32_e32 v128, v35
	v_mul_f32_e32 v35, v36, v37
	v_rcp_f32_e32 v49, v35
	v_mul_f32_e32 v50, v34, v193
	v_fma_f32 v34, -v128, v128, 1.0
	v_fmamk_f32 v47, v52, 0xbfb8aa3b, v99
	v_mul_f32_e32 v35, v37, v49
	v_mul_f32_e32 v35, v48, v35
	v_exp_f32_e32 v126, v35
	v_max_f32_e32 v34, 0, v34
	v_sqrt_f32_e32 v37, v34
	v_exp_f32_e32 v34, v129
	v_exp_f32_e32 v35, v47
	v_fma_f32 v47, -v126, v126, 1.0
	v_max_f32_e32 v47, 0, v47
	v_sqrt_f32_e32 v47, v47
	v_pk_add_f32 v[34:35], v[34:35], 1.0 op_sel_hi:[1,0]
	v_fmamk_f32 v52, v53, 0xbfb8aa3b, v99
	v_mul_f32_e32 v51, v34, v35
	v_rcp_f32_e32 v51, v51
	v_mul_f32_e32 v36, v36, v49
	v_mul_f32_e32 v129, v50, v37
	v_mul_f32_e32 v127, v36, v47
	v_exp_f32_e32 v36, v166
	v_exp_f32_e32 v37, v52
	v_mul_f32_e32 v35, v35, v51
	v_mul_f32_e32 v35, v48, v35
	s_waitcnt vmcnt(6)
	v_mfma_f32_32x32x16_bf16 v[18:33], v[66:69], v[174:177], v[18:33]
	v_add_f32_e64 v36, v36, 1.0
	v_add_f32_e64 v37, v37, 1.0
	v_fmamk_f32 v176, v62, 0xbfb8aa3b, v99
	v_exp_f32_e32 v62, v35
	v_mul_f32_e32 v35, v36, v37
	v_rcp_f32_e32 v47, v35
	v_fmamk_f32 v53, v54, 0xbfb8aa3b, v99
	v_mul_f32_e32 v49, v34, v51
	v_fma_f32 v34, -v62, v62, 1.0
	v_mul_f32_e32 v35, v37, v47
	v_mul_f32_e32 v35, v48, v35
	v_exp_f32_e32 v54, v35
	v_max_f32_e32 v34, 0, v34
	v_sqrt_f32_e32 v37, v34
	v_exp_f32_e32 v34, v38
	v_exp_f32_e32 v35, v53
	v_fma_f32 v38, -v54, v54, 1.0
	v_max_f32_e32 v38, 0, v38
	v_sqrt_f32_e32 v38, v38
	v_pk_add_f32 v[34:35], v[34:35], 1.0 op_sel_hi:[1,0]
	v_fmamk_f32 v169, v55, 0xbfb8aa3b, v99
	v_mul_f32_e32 v50, v34, v35
	v_rcp_f32_e32 v51, v50
	v_mul_f32_e32 v36, v36, v47
	v_fmamk_f32 v177, v63, 0xbfb8aa3b, v99
	v_mul_f32_e32 v63, v49, v37
	v_mul_f32_e32 v55, v36, v38
	v_exp_f32_e32 v36, v39
	v_exp_f32_e32 v37, v169
	v_mul_f32_e32 v35, v35, v51
	v_mul_f32_e32 v35, v48, v35
	v_exp_f32_e32 v50, v35
	v_pk_add_f32 v[36:37], v[36:37], 1.0 op_sel_hi:[1,0]
	v_mul_f32_e32 v39, v34, v51
	v_mul_f32_e32 v35, v36, v37
	v_rcp_f32_e32 v38, v35
	v_fma_f32 v34, -v50, v50, 1.0
	v_fmamk_f32 v56, v56, 0xbfb8aa3b, v99
	v_max_f32_e32 v34, 0, v34
	v_mul_f32_e32 v35, v37, v38
	v_mul_f32_e32 v35, v48, v35
	v_exp_f32_e32 v52, v35
	v_sqrt_f32_e32 v37, v34
	v_exp_f32_e32 v34, v40
	v_exp_f32_e32 v35, v56
	v_fma_f32 v40, -v52, v52, 1.0
	v_max_f32_e32 v40, 0, v40
	v_sqrt_f32_e32 v40, v40
	v_pk_add_f32 v[34:35], v[34:35], 1.0 op_sel_hi:[1,0]
	v_fmamk_f32 v57, v57, 0xbfb8aa3b, v99
	v_mul_f32_e32 v47, v34, v35
	v_rcp_f32_e32 v47, v47
	v_mul_f32_e32 v36, v36, v38
	v_mul_f32_e32 v51, v39, v37
	v_mul_f32_e32 v53, v36, v40
	v_exp_f32_e32 v36, v41
	v_exp_f32_e32 v37, v57
	v_mul_f32_e32 v35, v35, v47
	v_mul_f32_e32 v35, v48, v35
	v_exp_f32_e32 v56, v35
	v_pk_add_f32 v[36:37], v[36:37], 1.0 op_sel_hi:[1,0]
	v_fmamk_f32 v174, v58, 0xbfb8aa3b, v99
; #define MFMA32(a, b, c) __builtin_amdgcn_mfma_f32_32x32x16_bf16((a), (b), (c), 0, 0, 0)
; template <int DIR, int MODE> ...
;     ...
;         const bf16* wr_ = wl + (size_t)((DIR * 8 + w) * 2) * 4096 + (nt * 32 + r32) * 64 + 8 * h;
; #pragma unroll
;         for (int ks = 0; ks < 4; ++ks) {
;             const bf16x8 bR = *(const bf16x8*)(wr_ + 16 * ks), bI = *(const bf16x8*)(wr_ + 4096 + 16 * ks);
;             accR[nt] = MFMA32(af[ks], bR, accR[nt]); accI[nt] = MFMA32(af[ks], bI, accI[nt]); }
;     }
; #pragma unroll
;     for (int nt = 0; nt < 2; ++nt) {
;         const float nba = prm[DIR][nt][0], nbx = prm[DIR][nt][1], k8l = prm[DIR][nt][2];
; #pragma unroll
;         for (int i = 0; i < 16; ++i) {
;             const float d1 = 1.f + __builtin_amdgcn_exp2f(__builtin_fmaf(accR[nt][i], -1.4426950408889634f, nba));
;             const float d2 = 1.f + __builtin_amdgcn_exp2f(__builtin_fmaf(accI[nt][i], -1.4426950408889634f, nbx));
;             const float inv = __builtin_amdgcn_rcpf(d1 * d2), rr = inv * d2, ii = inv * d1;
;             const float av = __builtin_amdgcn_exp2f(k8l * rr);
;             accR[nt][i] = av; accI[nt][i] = __builtin_amdgcn_sqrtf(fmaxf(__builtin_fmaf(-av, av, 1.f), 0.f)) * ii; }
	v_mul_f32_e32 v35, v36, v37
	v_rcp_f32_e32 v40, v35
	v_mul_f32_e32 v41, v34, v47
	v_fma_f32 v34, -v56, v56, 1.0
	v_max_f32_e32 v34, 0, v34
	v_mul_f32_e32 v35, v37, v40
	v_mul_f32_e32 v35, v48, v35
	v_exp_f32_e32 v58, v35
	v_sqrt_f32_e32 v37, v34
	v_exp_f32_e32 v34, v42
	v_exp_f32_e32 v35, v174
	v_fma_f32 v38, -v58, v58, 1.0
	v_max_f32_e32 v38, 0, v38
	v_sqrt_f32_e32 v42, v38
	v_pk_add_f32 v[38:39], v[34:35], 1.0 op_sel_hi:[1,0]
	v_fmamk_f32 v175, v59, 0xbfb8aa3b, v99
	v_mul_f32_e32 v34, v38, v39
	v_rcp_f32_e32 v35, v34
	v_mul_f32_e32 v57, v41, v37
	v_mul_f32_e32 v34, v36, v40
	v_exp_f32_e32 v36, v43
	v_exp_f32_e32 v37, v175
	v_mul_f32_e32 v59, v34, v42
	v_mul_f32_e32 v34, v39, v35
	v_mul_f32_e32 v34, v48, v34
	v_pk_add_f32 v[40:41], v[36:37], 1.0 op_sel_hi:[1,0]
	v_exp_f32_e32 v34, v34
	v_mul_f32_e32 v36, v40, v41
	v_rcp_f32_e32 v37, v36
	v_mul_f32_e32 v35, v38, v35
	v_fma_f32 v36, -v34, v34, 1.0
	v_max_f32_e32 v38, 0, v36
	v_mul_f32_e32 v36, v41, v37
	v_mul_f32_e32 v36, v48, v36
	v_exp_f32_e32 v36, v36
	v_fmamk_f32 v60, v60, 0xbfb8aa3b, v99
	v_sqrt_f32_e32 v41, v38
	v_exp_f32_e32 v38, v44
	v_exp_f32_e32 v39, v60
	v_fma_f32 v42, -v36, v36, 1.0
	v_max_f32_e32 v42, 0, v42
	v_sqrt_f32_e32 v44, v42
	v_pk_add_f32 v[42:43], v[38:39], 1.0 op_sel_hi:[1,0]
	v_fmamk_f32 v61, v61, 0xbfb8aa3b, v99
	v_mul_f32_e32 v38, v42, v43
	v_rcp_f32_e32 v39, v38
	v_mul_f32_e32 v35, v35, v41
	v_mul_f32_e32 v37, v40, v37
	v_exp_f32_e32 v40, v45
	v_exp_f32_e32 v41, v61
	v_mul_f32_e32 v38, v43, v39
	v_mul_f32_e32 v37, v37, v44
	v_mul_f32_e32 v38, v48, v38
	v_pk_add_f32 v[44:45], v[40:41], 1.0 op_sel_hi:[1,0]
	v_exp_f32_e32 v38, v38
	v_mul_f32_e32 v40, v44, v45
	v_rcp_f32_e32 v41, v40
	v_mul_f32_e32 v39, v42, v39
	v_fma_f32 v40, -v38, v38, 1.0
	v_max_f32_e32 v42, 0, v40
	v_mul_f32_e32 v40, v45, v41
	v_mul_f32_e32 v40, v48, v40
	v_exp_f32_e32 v40, v40
	v_sqrt_f32_e32 v45, v42
	v_exp_f32_e32 v42, v46
	v_exp_f32_e32 v43, v176
	v_fma_f32 v46, -v40, v40, 1.0
	s_waitcnt vmcnt(3)
	v_mfma_f32_32x32x16_bf16 v[2:17], v[70:73], v[4:7], 0
	v_max_f32_e32 v46, 0, v46
	v_sqrt_f32_e32 v49, v46
	v_pk_add_f32 v[46:47], v[42:43], 1.0 op_sel_hi:[1,0]
	v_mul_f32_e32 v39, v39, v45
	v_mul_f32_e32 v42, v46, v47
	v_rcp_f32_e32 v43, v42
	v_mul_f32_e32 v41, v44, v41
	v_exp_f32_e32 v44, v167
	v_exp_f32_e32 v45, v177
	v_mul_f32_e32 v42, v47, v43
	s_waitcnt vmcnt(2)
	v_mfma_f32_32x32x16_bf16 v[2:17], v[66:69], v[178:181], v[2:17]
	v_mul_f32_e32 v42, v48, v42
	v_add_f32_e64 v60, v44, 1.0
	v_add_f32_e64 v61, v45, 1.0
	v_exp_f32_e32 v42, v42
	v_mul_f32_e32 v44, v60, v61
	v_rcp_f32_e32 v45, v44
	v_mul_f32_e32 v43, v46, v43
	v_fma_f32 v44, -v42, v42, 1.0
	v_max_f32_e32 v46, 0, v44
	v_mul_f32_e32 v44, v61, v45
	v_mul_f32_e32 v44, v48, v44
	v_mfma_f32_32x32x16_bf16 v[18:33], v[78:81], v[182:185], v[18:33]
	v_exp_f32_e32 v44, v44
	v_fmamk_f32 v64, v64, 0xbfb8aa3b, v99
	v_mul_f32_e32 v41, v41, v49
	v_sqrt_f32_e32 v49, v46
	v_exp_f32_e32 v46, v168
	v_exp_f32_e32 v47, v64
	v_fma_f32 v61, -v44, v44, 1.0
	s_waitcnt vmcnt(1)
	v_mfma_f32_32x32x16_bf16 v[2:17], v[78:81], v[186:189], v[2:17]
	v_max_f32_e32 v61, 0, v61
	v_sqrt_f32_e32 v61, v61
	v_pk_add_f32 v[46:47], v[46:47], 1.0 op_sel_hi:[1,0]
	v_fmac_f32_e32 v99, 0xbfb8aa3b, v65
	v_mul_f32_e32 v64, v46, v47
	v_mul_f32_e32 v45, v60, v45
	v_rcp_f32_e32 v64, v64
	v_mfma_f32_32x32x16_bf16 v[18:33], v[74:77], v[170:173], v[18:33]
	v_mul_f32_e32 v45, v45, v61
	v_exp_f32_e32 v60, v97
	v_exp_f32_e32 v61, v99
	v_mul_f32_e32 v47, v47, v64
	v_mul_f32_e32 v43, v43, v49
	v_mul_f32_e32 v49, v46, v64
	v_pk_add_f32 v[60:61], v[60:61], 1.0 op_sel_hi:[1,0]
	s_waitcnt vmcnt(0)
	v_mfma_f32_32x32x16_bf16 v[2:17], v[74:77], v[200:203], v[2:17]
	v_mul_f32_e32 v46, v48, v47
	v_mul_f32_e32 v47, v60, v61
	v_rcp_f32_e32 v97, v47
	v_fmamk_f32 v18, v18, 0xbfb8aa3b, v95
	v_exp_f32_e32 v46, v46
	v_exp_f32_e32 v64, v18
	v_mul_f32_e32 v61, v61, v97
	s_nop 4
	v_fmamk_f32 v2, v2, 0xbfb8aa3b, v93
	v_exp_f32_e32 v65, v2
	v_fma_f32 v47, -v46, v46, 1.0
	v_mul_f32_e32 v48, v48, v61
	v_max_f32_e32 v47, 0, v47
	v_pk_add_f32 v[64:65], v[64:65], 1.0 op_sel_hi:[1,0]
	v_exp_f32_e32 v48, v48
	v_mul_f32_e32 v18, v64, v65
	v_sqrt_f32_e32 v47, v47
	v_rcp_f32_e32 v193, v18
	v_fma_f32 v2, -v48, v48, 1.0
	v_mov_b32_e32 v125, v65
	v_mul_f32_e32 v47, v49, v47
	v_mul_f32_e32 v49, v60, v97
	v_max_f32_e32 v2, 0, v2
	v_pk_mul_f32 v[60:61], v[124:125], v[192:193]
	v_sqrt_f32_e32 v97, v2
	v_mul_f32_e32 v2, v60, v61
	v_exp_f32_e32 v2, v2
	v_fmamk_f32 v18, v19, 0xbfb8aa3b, v95
	v_fmamk_f32 v3, v3, 0xbfb8aa3b, v93
	v_exp_f32_e32 v18, v18
	v_exp_f32_e32 v19, v3
	v_fma_f32 v3, -v2, v2, 1.0
	v_max_f32_e32 v3, 0, v3
	v_sqrt_f32_e32 v3, v3
	v_pk_add_f32 v[18:19], v[18:19], 1.0 op_sel_hi:[1,0]
	v_mul_f32_e32 v64, v64, v193
	v_mul_f32_e32 v61, v18, v19
	v_rcp_f32_e32 v61, v61
	v_fmamk_f32 v20, v20, 0xbfb8aa3b, v95
	v_fmamk_f32 v4, v4, 0xbfb8aa3b, v93
	v_mul_f32_e32 v3, v64, v3
	v_exp_f32_e32 v64, v20
	v_exp_f32_e32 v65, v4
	v_mul_f32_e32 v19, v19, v61
	v_mul_f32_e32 v4, v60, v19
	v_mul_f32_e32 v20, v18, v61
	v_exp_f32_e32 v166, v4
	v_pk_add_f32 v[18:19], v[64:65], 1.0 op_sel_hi:[1,0]
	v_fmamk_f32 v5, v5, 0xbfb8aa3b, v93
	v_mul_f32_e32 v4, v18, v19
	v_rcp_f32_e32 v61, v4
	v_fma_f32 v4, -v166, v166, 1.0
	v_max_f32_e32 v4, 0, v4
	v_sqrt_f32_e32 v65, v4
	v_mul_f32_e32 v4, v19, v61
	v_mul_f32_e32 v4, v60, v4
	v_exp_f32_e32 v64, v4
	v_fmamk_f32 v4, v21, 0xbfb8aa3b, v95
	v_exp_f32_e32 v4, v4
	v_exp_f32_e32 v5, v5
	v_fma_f32 v19, -v64, v64, 1.0
	v_max_f32_e32 v19, 0, v19
	v_sqrt_f32_e32 v19, v19
	v_pk_add_f32 v[4:5], v[4:5], 1.0 op_sel_hi:[1,0]
	v_mul_f32_e32 v49, v49, v97
	v_mul_f32_e32 v21, v4, v5
	v_rcp_f32_e32 v97, v21
; __device__ __forceinline__ unsigned cvt_pk_bf16(float lo, float hi) { unsigned r; asm volatile("v_cvt_pk_bf16_f32 %0, %1, %2" : "=v"(r) : "v"(lo), "v"(hi)); return r; }
; #define LAS __attribute__((address_space(3)))
; #define LDS_WAVE_SYNC() asm volatile("s_waitcnt lgkmcnt(0)" ::: "memory")
; template <int DIR, int MODE> ...
;     ...
;     for (int nt = 0; nt < 2; ++nt) {
;         const float nba = prm[DIR][nt][0], nbx = prm[DIR][nt][1], k8l = prm[DIR][nt][2];
; #pragma unroll
;         for (int i = 0; i < 16; ++i) {
;             const float d1 = 1.f + __builtin_amdgcn_exp2f(__builtin_fmaf(accR[nt][i], -1.4426950408889634f, nba));
;             const float d2 = 1.f + __builtin_amdgcn_exp2f(__builtin_fmaf(accI[nt][i], -1.4426950408889634f, nbx));
;             const float inv = __builtin_amdgcn_rcpf(d1 * d2), rr = inv * d2, ii = inv * d1;
;             const float av = __builtin_amdgcn_exp2f(k8l * rr);
;             accR[nt][i] = av; accI[nt][i] = __builtin_amdgcn_sqrtf(fmaxf(__builtin_fmaf(-av, av, 1.f), 0.f)) * ii; }
;     }
;     float hc = 0.f, ap = 1.f;
;     if (MODE == 1) hc = ((const float*)(a.ws + WS_CAR))[(size_t)((b * NCH + ch) * 2 + DIR) * LW + c];
; #pragma unroll
;     for (int hh = 0; hh < 2; ++hh) {
;         const int half = DIR == 0 ? hh : 1 - hh;
; #pragma unroll
;         for (int nt = 0; nt < 2; ++nt)
; #pragma unroll
;             for (int i = 0; i < 8; ++i) { const int tt = 8 * (i >> 2) + 4 * h + (i & 3);
;                 f32x2 v; v.x = accR[nt][8 * half + i]; v.y = accI[nt][8 * half + i];
;                 *(LAS f32x2*)(au + (tt * 64 + nt * 32 + r32) * 2) = v; }
;         LDS_WAVE_SYNC();
; #pragma unroll
;         for (int s = 0; s < 16; ++s) {
;             const int tt = DIR == 0 ? s : 15 - s, t = half * 16 + tt;
;             const f32x2 v = *(const LAS f32x2*)(au + (tt * 64 + lane) * 2);
;             hc = v.x * hc + v.y * xcr[t];
;             if (MODE == 0) { ap *= v.x;
;                 ((unsigned*)(a.ws + WS_HP))[((size_t)DIR * T + (size_t)b * SEQ + ch * 32 + t) * LW + c] = pg8::cvt_pk_bf16(hc, ap); }
;             if (MODE == 1) { if (DIR == 0) hf[t] = hc; else hf[t] = gl[t] * (hf[t] + hc); }
;         }
	v_mul_f32_e32 v18, v18, v61
	v_mul_f32_e32 v167, v20, v65
	v_mul_f32_e32 v65, v18, v19
	v_fmamk_f32 v18, v22, 0xbfb8aa3b, v95
	v_fmamk_f32 v6, v6, 0xbfb8aa3b, v93
	v_exp_f32_e32 v20, v18
	v_exp_f32_e32 v21, v6
	v_mul_f32_e32 v5, v5, v97
	v_mul_f32_e32 v19, v4, v97
	v_mul_f32_e32 v4, v60, v5
	v_exp_f32_e32 v18, v4
	v_pk_add_f32 v[4:5], v[20:21], 1.0 op_sel_hi:[1,0]
	v_fmamk_f32 v9, v9, 0xbfb8aa3b, v93
	v_mul_f32_e32 v6, v4, v5
	v_rcp_f32_e32 v61, v6
	v_fma_f32 v6, -v18, v18, 1.0
	v_max_f32_e32 v6, 0, v6
	v_sqrt_f32_e32 v22, v6
	v_mul_f32_e32 v5, v5, v61
	v_mul_f32_e32 v5, v60, v5
	v_fmamk_f32 v6, v23, 0xbfb8aa3b, v95
	v_exp_f32_e32 v20, v6
	v_exp_f32_e32 v6, v5
	v_fmamk_f32 v5, v7, 0xbfb8aa3b, v93
	v_exp_f32_e32 v21, v5
	v_mul_f32_e32 v19, v19, v22
	v_fma_f32 v5, -v6, v6, 1.0
	v_max_f32_e32 v5, 0, v5
	v_pk_add_f32 v[20:21], v[20:21], 1.0 op_sel_hi:[1,0]
	v_sqrt_f32_e32 v5, v5
	v_mul_f32_e32 v7, v20, v21
	v_rcp_f32_e32 v97, v7
	v_fmamk_f32 v7, v24, 0xbfb8aa3b, v95
	v_exp_f32_e32 v22, v7
	v_fmamk_f32 v7, v8, 0xbfb8aa3b, v93
	v_exp_f32_e32 v23, v7
	v_mul_f32_e32 v4, v4, v61
	v_mul_f32_e32 v7, v4, v5
	v_mul_f32_e32 v8, v21, v97
	v_pk_add_f32 v[4:5], v[22:23], 1.0 op_sel_hi:[1,0]
	v_mul_f32_e32 v8, v60, v8
	v_mul_f32_e32 v21, v4, v5
	v_rcp_f32_e32 v21, v21
	v_mul_f32_e32 v24, v20, v97
	v_exp_f32_e32 v8, v8
	v_exp_f32_e32 v23, v9
	v_mul_f32_e32 v5, v5, v21
	v_mul_f32_e32 v5, v60, v5
	v_exp_f32_e32 v20, v5
	v_fma_f32 v5, -v8, v8, 1.0
	v_max_f32_e32 v5, 0, v5
	v_sqrt_f32_e32 v5, v5
	v_fma_f32 v22, -v20, v20, 1.0
	v_max_f32_e32 v22, 0, v22
	v_sqrt_f32_e32 v61, v22
	v_fmamk_f32 v22, v25, 0xbfb8aa3b, v95
	v_exp_f32_e32 v22, v22
	v_mul_f32_e32 v4, v4, v21
	v_mul_f32_e32 v9, v24, v5
	v_mul_f32_e32 v21, v4, v61
	v_pk_add_f32 v[4:5], v[22:23], 1.0 op_sel_hi:[1,0]
	v_lshlrev_b32_e32 v23, 11, v165
	v_lshlrev_b32_e32 v24, 3, v164
	v_mul_f32_e32 v22, v4, v5
	v_add3_u32 v24, s0, v23, v24
	v_rcp_f32_e32 v22, v22
	v_add_u32_e32 v124, 0x1000, v24
	ds_write2_b64 v124, v[128:129], v[2:3] offset0:64 offset1:96
	v_fmamk_f32 v2, v26, 0xbfb8aa3b, v95
	v_fmamk_f32 v3, v10, 0xbfb8aa3b, v93
	v_exp_f32_e32 v2, v2
	v_exp_f32_e32 v3, v3
	v_mul_f32_e32 v5, v5, v22
	v_mul_f32_e32 v5, v60, v5
	v_exp_f32_e32 v10, v5
	v_mul_f32_e32 v25, v4, v22
	v_pk_add_f32 v[4:5], v[2:3], 1.0 op_sel_hi:[1,0]
	v_fmamk_f32 v13, v13, 0xbfb8aa3b, v93
	v_mul_f32_e32 v2, v4, v5
	v_rcp_f32_e32 v3, v2
	v_fma_f32 v2, -v10, v10, 1.0
	v_max_f32_e32 v2, 0, v2
	v_sqrt_f32_e32 v61, v2
	v_mul_f32_e32 v2, v5, v3
	v_fmamk_f32 v5, v27, 0xbfb8aa3b, v95
	v_mul_f32_e32 v2, v60, v2
	v_exp_f32_e32 v22, v5
	v_fmamk_f32 v5, v11, 0xbfb8aa3b, v93
	v_exp_f32_e32 v2, v2
	v_exp_f32_e32 v23, v5
	v_mul_f32_e32 v3, v4, v3
	v_fmamk_f32 v14, v14, 0xbfb8aa3b, v93
	v_fma_f32 v5, -v2, v2, 1.0
	v_pk_add_f32 v[26:27], v[22:23], 1.0 op_sel_hi:[1,0]
	v_max_f32_e32 v5, 0, v5
	v_mul_f32_e32 v11, v26, v27
	v_sqrt_f32_e32 v5, v5
	v_rcp_f32_e32 v97, v11
	v_mul_f32_e32 v11, v25, v61
	ds_write2_b64 v124, v[126:127], v[166:167] offset0:128 offset1:160
	v_mul_f32_e32 v3, v3, v5
	v_mul_f32_e32 v4, v27, v97
	v_fmamk_f32 v5, v28, 0xbfb8aa3b, v95
	v_mul_f32_e32 v4, v60, v4
	v_exp_f32_e32 v22, v5
	v_fmamk_f32 v5, v12, 0xbfb8aa3b, v93
	v_exp_f32_e32 v4, v4
	v_exp_f32_e32 v23, v5
	v_exp_f32_e32 v27, v13
	v_add_u32_e32 v126, 0x1800, v24
	v_fma_f32 v5, -v4, v4, 1.0
	v_pk_add_f32 v[22:23], v[22:23], 1.0 op_sel_hi:[1,0]
	v_max_f32_e32 v5, 0, v5
	v_mul_f32_e32 v12, v22, v23
	v_sqrt_f32_e32 v5, v5
	v_rcp_f32_e32 v25, v12
	v_mul_f32_e32 v12, v26, v97
	ds_write2_b64 v126, v[54:55], v[18:19] offset1:32
	v_mul_f32_e32 v5, v12, v5
	v_mul_f32_e32 v12, v23, v25
	v_fmamk_f32 v23, v29, 0xbfb8aa3b, v95
	v_exp_f32_e32 v26, v23
	v_mul_f32_e32 v12, v60, v12
	v_exp_f32_e32 v12, v12
	v_mul_f32_e32 v22, v22, v25
	v_pk_add_f32 v[26:27], v[26:27], 1.0 op_sel_hi:[1,0]
	v_exp_f32_e32 v29, v14
	v_mul_f32_e32 v23, v26, v27
	v_fma_f32 v13, -v12, v12, 1.0
	v_rcp_f32_e32 v28, v23
	v_max_f32_e32 v13, 0, v13
	v_sqrt_f32_e32 v13, v13
	v_fmamk_f32 v18, v31, 0xbfb8aa3b, v95
	v_mul_f32_e32 v23, v27, v28
	v_mul_f32_e32 v23, v60, v23
	v_mul_f32_e32 v13, v22, v13
	v_mul_f32_e32 v22, v26, v28
	v_exp_f32_e32 v26, v23
	v_fmamk_f32 v23, v30, 0xbfb8aa3b, v95
	v_exp_f32_e32 v28, v23
	v_fmamk_f32 v15, v15, 0xbfb8aa3b, v93
	v_fma_f32 v14, -v26, v26, 1.0
	v_max_f32_e32 v14, 0, v14
	v_pk_add_f32 v[28:29], v[28:29], 1.0 op_sel_hi:[1,0]
	v_exp_f32_e32 v18, v18
	v_mul_f32_e32 v23, v28, v29
	v_exp_f32_e32 v19, v15
	v_sqrt_f32_e32 v14, v14
	v_rcp_f32_e32 v23, v23
	v_add_u32_e32 v127, 0x2000, v24
	v_add_u32_e32 v128, 0x2800, v24
	ds_write2_b64 v124, v[62:63], v[64:65] offset0:192 offset1:224
	ds_write2_b64 v127, v[50:51], v[6:7] offset0:64 offset1:96
	ds_write2_b64 v127, v[52:53], v[8:9] offset0:128 offset1:160
	ds_write2_b64 v127, v[56:57], v[20:21] offset0:192 offset1:224
	ds_write2_b64 v128, v[58:59], v[10:11] offset1:32
	v_lshl_add_u32 v125, v84, 3, s0
	v_pk_add_f32 v[18:19], v[18:19], 1.0 op_sel_hi:[1,0]
	s_waitcnt lgkmcnt(0)
	v_mul_f32_e32 v27, v22, v14
	v_mul_f32_e32 v14, v29, v23
	v_mul_f32_e32 v22, v28, v23
	v_mul_f32_e32 v23, v18, v19
	ds_read_b64 v[8:9], v125 offset:4608
	v_rcp_f32_e32 v23, v23
	v_mov_b32_e32 v84, v1
	v_mul_f32_e32 v14, v60, v14
	v_exp_f32_e32 v14, v14
	v_mul_f32_e32 v7, v18, v23
	s_waitcnt lgkmcnt(0)
	v_mul_f32_e32 v18, v85, v9
	v_mul_f32_e32 v6, v19, v23
	v_pk_fma_f32 v[18:19], v[84:85], v[8:9], v[18:19] op_sel_hi:[1,1,0]
	v_fma_f32 v15, -v14, v14, 1.0
	v_cvt_pk_bf16_f32 v19, v18, v8
	ds_read_b64 v[20:21], v125 offset:5120
	v_mul_f32_e32 v6, v60, v6
	v_max_f32_e32 v15, 0, v15
	v_exp_f32_e32 v6, v6
	v_fmamk_f32 v11, v16, 0xbfb8aa3b, v93
	global_store_dword v[122:123], v19, off
	v_mov_b32_e32 v19, v0
	s_waitcnt lgkmcnt(0)
; __device__ __forceinline__ unsigned cvt_pk_bf16(float lo, float hi) { unsigned r; asm volatile("v_cvt_pk_bf16_f32 %0, %1, %2" : "=v"(r) : "v"(lo), "v"(hi)); return r; }
; #define LAS __attribute__((address_space(3)))
; #define LDS_WAVE_SYNC() asm volatile("s_waitcnt lgkmcnt(0)" ::: "memory")
; template <int DIR, int MODE> ...
;     ...
;             for (int i = 0; i < 8; ++i) { const int tt = 8 * (i >> 2) + 4 * h + (i & 3);
;                 f32x2 v; v.x = accR[nt][8 * half + i]; v.y = accI[nt][8 * half + i];
;                 *(LAS f32x2*)(au + (tt * 64 + nt * 32 + r32) * 2) = v; }
;         LDS_WAVE_SYNC();
; #pragma unroll
;         for (int s = 0; s < 16; ++s) {
;             const int tt = DIR == 0 ? s : 15 - s, t = half * 16 + tt;
;             const f32x2 v = *(const LAS f32x2*)(au + (tt * 64 + lane) * 2);
;             hc = v.x * hc + v.y * xcr[t];
;             if (MODE == 0) { ap *= v.x;
;                 ((unsigned*)(a.ws + WS_HP))[((size_t)DIR * T + (size_t)b * SEQ + ch * 32 + t) * LW + c] = pg8::cvt_pk_bf16(hc, ap); }
;             if (MODE == 1) { if (DIR == 0) hf[t] = hc; else hf[t] = gl[t] * (hf[t] + hc); }
;         }
	v_mul_f32_e32 v16, v0, v21
	v_sqrt_f32_e32 v15, v15
	v_pk_fma_f32 v[18:19], v[18:19], v[20:21], v[16:17] op_sel_hi:[1,1,0]
	v_pk_mul_f32 v[8:9], v[8:9], v[20:21]
	v_fma_f32 v10, -v6, v6, 1.0
	v_cvt_pk_bf16_f32 v16, v18, v8
	ds_read_b64 v[20:21], v125 offset:5632
	v_mul_f32_e32 v15, v22, v15
	v_max_f32_e32 v22, 0, v10
	v_fmamk_f32 v10, v32, 0xbfb8aa3b, v95
	v_exp_f32_e32 v10, v10
	v_exp_f32_e32 v11, v11
	global_store_dword v[120:121], v16, off offset:2048
	v_mov_b32_e32 v19, v130
	s_waitcnt lgkmcnt(0)
	v_mul_f32_e32 v16, v130, v21
	v_pk_fma_f32 v[18:19], v[18:19], v[20:21], v[16:17] op_sel_hi:[1,1,0]
	v_pk_mul_f32 v[8:9], v[8:9], v[20:21]
	v_pk_add_f32 v[10:11], v[10:11], 1.0 op_sel_hi:[1,0]
	v_cvt_pk_bf16_f32 v16, v18, v8
	ds_read_b64 v[20:21], v125 offset:6144
	v_mul_f32_e32 v19, v10, v11
	v_rcp_f32_e32 v23, v19
	global_store_dword v[116:117], v16, off offset:-4096
	v_mov_b32_e32 v19, v131
	s_waitcnt lgkmcnt(0)
	v_mul_f32_e32 v16, v131, v21
	v_pk_fma_f32 v[18:19], v[18:19], v[20:21], v[16:17] op_sel_hi:[1,1,0]
	v_pk_mul_f32 v[8:9], v[8:9], v[20:21]
	v_mov_b32_e32 v19, v132
	v_cvt_pk_bf16_f32 v16, v18, v8
	ds_read_b64 v[20:21], v125 offset:6656
	global_store_dword v[118:119], v16, off offset:2048
	v_sqrt_f32_e32 v22, v22
	v_mul_f32_e32 v11, v11, v23
	v_mul_f32_e32 v11, v60, v11
	s_waitcnt lgkmcnt(0)
	v_mul_f32_e32 v16, v132, v21
	v_pk_fma_f32 v[18:19], v[18:19], v[20:21], v[16:17] op_sel_hi:[1,1,0]
	v_pk_mul_f32 v[8:9], v[8:9], v[20:21]
	v_mul_f32_e32 v7, v7, v22
	v_cvt_pk_bf16_f32 v19, v18, v8
	ds_read_b64 v[20:21], v125 offset:7168
	global_store_dword v[116:117], v19, off
	v_mov_b32_e32 v19, v133
	v_exp_f32_e32 v16, v11
	v_fmac_f32_e32 v95, 0xbfb8aa3b, v33
	s_waitcnt lgkmcnt(0)
	v_mul_f32_e32 v22, v133, v21
	v_pk_fma_f32 v[18:19], v[18:19], v[20:21], v[22:23] op_sel_hi:[1,1,0]
	v_pk_mul_f32 v[8:9], v[8:9], v[20:21]
	v_mul_f32_e32 v23, v10, v23
	v_cvt_pk_bf16_f32 v11, v18, v8
	ds_read_b64 v[20:21], v125 offset:7680
	v_mov_b32_e32 v19, v134
	global_store_dword v[116:117], v11, off offset:2048
	v_fmac_f32_e32 v93, 0xbfb8aa3b, v17
	v_add_co_u32_e32 v110, vcc, s1, v88
	s_waitcnt lgkmcnt(0)
	v_mul_f32_e32 v10, v134, v21
	v_pk_fma_f32 v[10:11], v[18:19], v[20:21], v[10:11] op_sel_hi:[1,1,0]
	v_pk_mul_f32 v[8:9], v[8:9], v[20:21]
	v_exp_f32_e32 v20, v95
	v_cvt_pk_bf16_f32 v11, v10, v8
	ds_read_b64 v[18:19], v125 offset:8192
	global_store_dword v[112:113], v11, off offset:-4096
	v_mov_b32_e32 v11, v135
	v_exp_f32_e32 v21, v93
	v_addc_co_u32_e32 v111, vcc, 0, v89, vcc
	s_waitcnt lgkmcnt(0)
	v_mul_f32_e32 v22, v135, v19
	v_pk_fma_f32 v[10:11], v[10:11], v[18:19], v[22:23] op_sel_hi:[1,1,0]
	v_pk_mul_f32 v[8:9], v[8:9], v[18:19]
	v_pk_add_f32 v[20:21], v[20:21], 1.0 op_sel_hi:[1,0]
	v_cvt_pk_bf16_f32 v11, v10, v8
	ds_read_b64 v[18:19], v125 offset:8704
	global_store_dword v[114:115], v11, off offset:2048
	v_mov_b32_e32 v11, v136
	s_mov_b32 s1, 0x11f06000
	v_add_co_u32_e32 v108, vcc, s1, v88
	s_waitcnt lgkmcnt(0)
	v_mul_f32_e32 v22, v136, v19
	v_pk_fma_f32 v[10:11], v[10:11], v[18:19], v[22:23] op_sel_hi:[1,1,0]
	v_pk_mul_f32 v[8:9], v[8:9], v[18:19]
	v_addc_co_u32_e32 v109, vcc, 0, v89, vcc
	v_cvt_pk_bf16_f32 v11, v10, v8
	ds_read_b64 v[18:19], v125 offset:9216
	global_store_dword v[112:113], v11, off
	v_mov_b32_e32 v11, v137
	v_fma_f32 v24, -v16, v16, 1.0
	v_max_f32_e32 v17, 0, v24
	s_waitcnt lgkmcnt(0)
	v_mul_f32_e32 v22, v137, v19
	v_pk_fma_f32 v[10:11], v[10:11], v[18:19], v[22:23] op_sel_hi:[1,1,0]
	v_pk_mul_f32 v[8:9], v[8:9], v[18:19]
	v_mul_f32_e32 v22, v20, v21
	v_cvt_pk_bf16_f32 v11, v10, v8
	ds_read_b64 v[18:19], v125 offset:9728
	v_rcp_f32_e32 v25, v22
	global_store_dword v[112:113], v11, off offset:2048
	v_mov_b32_e32 v11, v138
	s_mov_b32 s1, 0x11f07000
	s_waitcnt lgkmcnt(0)
	v_mul_f32_e32 v22, v138, v19
	v_pk_fma_f32 v[10:11], v[10:11], v[18:19], v[22:23] op_sel_hi:[1,1,0]
	v_pk_mul_f32 v[8:9], v[8:9], v[18:19]
	v_mul_f32_e32 v21, v21, v25
	v_cvt_pk_bf16_f32 v11, v10, v8
	ds_read_b64 v[18:19], v125 offset:10240
	global_store_dword v[108:109], v11, off offset:-4096
	v_mov_b32_e32 v11, v139
	v_mul_f32_e32 v21, v60, v21
	v_add_co_u32_e32 v106, vcc, s1, v88
	s_waitcnt lgkmcnt(0)
	v_mul_f32_e32 v22, v139, v19
	v_pk_fma_f32 v[10:11], v[10:11], v[18:19], v[22:23] op_sel_hi:[1,1,0]
	v_pk_mul_f32 v[8:9], v[8:9], v[18:19]
	v_exp_f32_e32 v22, v21
	v_cvt_pk_bf16_f32 v11, v10, v8
	ds_read_b64 v[18:19], v125 offset:10752
	global_store_dword v[110:111], v11, off offset:2048
	v_mov_b32_e32 v11, v140
	v_fma_f32 v21, -v22, v22, 1.0
	v_max_f32_e32 v21, 0, v21
	s_waitcnt lgkmcnt(0)
	v_mul_f32_e32 v24, v140, v19
	v_pk_fma_f32 v[10:11], v[10:11], v[18:19], v[24:25] op_sel_hi:[1,1,0]
	v_pk_mul_f32 v[8:9], v[8:9], v[18:19]
	v_sqrt_f32_e32 v17, v17
	v_cvt_pk_bf16_f32 v11, v10, v8
	ds_read_b64 v[18:19], v125 offset:11264
	global_store_dword v[108:109], v11, off
	v_mov_b32_e32 v11, v141
	v_sqrt_f32_e32 v21, v21
	v_addc_co_u32_e32 v107, vcc, 0, v89, vcc
	s_waitcnt lgkmcnt(0)
	v_mul_f32_e32 v24, v141, v19
	v_pk_fma_f32 v[10:11], v[10:11], v[18:19], v[24:25] op_sel_hi:[1,1,0]
	v_pk_mul_f32 v[8:9], v[8:9], v[18:19]
	s_mov_b32 s1, 0x11f08000
	v_cvt_pk_bf16_f32 v11, v10, v8
	ds_read_b64 v[18:19], v125 offset:11776
	global_store_dword v[108:109], v11, off offset:2048
	v_mov_b32_e32 v11, v142
	v_add_co_u32_e32 v104, vcc, s1, v88
	s_waitcnt lgkmcnt(0)
	v_mul_f32_e32 v24, v142, v19
	v_pk_fma_f32 v[10:11], v[10:11], v[18:19], v[24:25] op_sel_hi:[1,1,0]
	v_pk_mul_f32 v[8:9], v[8:9], v[18:19]
	v_addc_co_u32_e32 v105, vcc, 0, v89, vcc
	v_cvt_pk_bf16_f32 v11, v10, v8
	ds_read_b64 v[18:19], v125 offset:12288
	v_mul_f32_e32 v20, v20, v25
	v_mul_f32_e32 v17, v23, v17
	v_mul_f32_e32 v23, v20, v21
	global_store_dword v[104:105], v11, off offset:-4096
	v_mov_b32_e32 v11, v143
	s_waitcnt lgkmcnt(0)
; __device__ __forceinline__ unsigned cvt_pk_bf16(float lo, float hi) { unsigned r; asm volatile("v_cvt_pk_bf16_f32 %0, %1, %2" : "=v"(r) : "v"(lo), "v"(hi)); return r; }
; #define LAS __attribute__((address_space(3)))
; #define LDS_WAVE_SYNC() asm volatile("s_waitcnt lgkmcnt(0)" ::: "memory")
; template <int DIR, int MODE> ...
;     ...
;     for (int hh = 0; hh < 2; ++hh) {
;         const int half = DIR == 0 ? hh : 1 - hh;
; #pragma unroll
;         for (int nt = 0; nt < 2; ++nt)
; #pragma unroll
;             for (int i = 0; i < 8; ++i) { const int tt = 8 * (i >> 2) + 4 * h + (i & 3);
;                 f32x2 v; v.x = accR[nt][8 * half + i]; v.y = accI[nt][8 * half + i];
;                 *(LAS f32x2*)(au + (tt * 64 + nt * 32 + r32) * 2) = v; }
;         LDS_WAVE_SYNC();
; #pragma unroll
;         for (int s = 0; s < 16; ++s) {
;             const int tt = DIR == 0 ? s : 15 - s, t = half * 16 + tt;
;             const f32x2 v = *(const LAS f32x2*)(au + (tt * 64 + lane) * 2);
;             hc = v.x * hc + v.y * xcr[t];
;             if (MODE == 0) { ap *= v.x;
;                 ((unsigned*)(a.ws + WS_HP))[((size_t)DIR * T + (size_t)b * SEQ + ch * 32 + t) * LW + c] = pg8::cvt_pk_bf16(hc, ap); }
;             if (MODE == 1) { if (DIR == 0) hf[t] = hc; else hf[t] = gl[t] * (hf[t] + hc); }
;         }
	v_mul_f32_e32 v20, v143, v19
	v_pk_fma_f32 v[10:11], v[10:11], v[18:19], v[20:21] op_sel_hi:[1,1,0]
	v_pk_mul_f32 v[8:9], v[8:9], v[18:19]
	v_cvt_pk_bf16_f32 v11, v10, v8
	global_store_dword v[106:107], v11, off offset:2048
	s_waitcnt lgkmcnt(0)
	ds_write2_b64 v124, v[34:35], v[2:3] offset0:64 offset1:96
	ds_write2_b64 v124, v[36:37], v[4:5] offset0:128 offset1:160
	ds_write2_b64 v124, v[38:39], v[12:13] offset0:192 offset1:224
	ds_write2_b64 v126, v[40:41], v[26:27] offset1:32
	ds_write2_b64 v127, v[42:43], v[14:15] offset0:64 offset1:96
	ds_write2_b64 v127, v[44:45], v[6:7] offset0:128 offset1:160
	ds_write2_b64 v127, v[46:47], v[16:17] offset0:192 offset1:224
	ds_write2_b64 v128, v[48:49], v[22:23] offset1:32
	s_waitcnt lgkmcnt(0)
	ds_read_b64 v[2:3], v125 offset:4608
	v_mov_b32_e32 v11, v144
	s_mov_b32 s1, 0x11f0a000
	s_waitcnt lgkmcnt(0)
	v_mul_f32_e32 v6, v144, v3
	v_pk_fma_f32 v[6:7], v[10:11], v[2:3], v[6:7] op_sel_hi:[1,1,0]
	v_pk_mul_f32 v[2:3], v[8:9], v[2:3]
	v_cvt_pk_bf16_f32 v7, v6, v2
	ds_read_b64 v[8:9], v125 offset:5120
	global_store_dword v[104:105], v7, off
	v_mov_b32_e32 v7, v145
	v_add_co_u32_e32 v10, vcc, s1, v88
	s_waitcnt lgkmcnt(0)
	v_mul_f32_e32 v4, v145, v9
	v_pk_fma_f32 v[6:7], v[6:7], v[8:9], v[4:5] op_sel_hi:[1,1,0]
	v_pk_mul_f32 v[2:3], v[2:3], v[8:9]
	v_mov_b32_e32 v7, v146
	v_cvt_pk_bf16_f32 v4, v6, v2
	ds_read_b64 v[8:9], v125 offset:5632
	global_store_dword v[104:105], v4, off offset:2048
	v_addc_co_u32_e32 v11, vcc, 0, v89, vcc
	s_mov_b32 s0, 0x11f09000
	s_waitcnt lgkmcnt(0)
	v_mul_f32_e32 v4, v146, v9
	v_pk_fma_f32 v[6:7], v[6:7], v[8:9], v[4:5] op_sel_hi:[1,1,0]
	v_pk_mul_f32 v[2:3], v[2:3], v[8:9]
	v_mov_b32_e32 v7, v147
	v_cvt_pk_bf16_f32 v4, v6, v2
	ds_read_b64 v[8:9], v125 offset:6144
	global_store_dword v[10:11], v4, off offset:-4096
	v_add_co_u32_e32 v12, vcc, s0, v88
	s_mov_b32 s1, 0x11f0c000
	s_waitcnt lgkmcnt(0)
	v_mul_f32_e32 v4, v147, v9
	v_pk_fma_f32 v[6:7], v[6:7], v[8:9], v[4:5] op_sel_hi:[1,1,0]
	v_pk_mul_f32 v[2:3], v[2:3], v[8:9]
	v_addc_co_u32_e32 v13, vcc, 0, v89, vcc
	v_cvt_pk_bf16_f32 v4, v6, v2
	ds_read_b64 v[8:9], v125 offset:6656
	global_store_dword v[12:13], v4, off offset:2048
	v_mov_b32_e32 v7, v148
	s_mov_b32 s0, 0x11f0b000
	s_waitcnt lgkmcnt(0)
	v_mul_f32_e32 v4, v148, v9
	v_pk_fma_f32 v[6:7], v[6:7], v[8:9], v[4:5] op_sel_hi:[1,1,0]
	v_pk_mul_f32 v[2:3], v[2:3], v[8:9]
	v_cvt_pk_bf16_f32 v4, v6, v2
	ds_read_b64 v[8:9], v125 offset:7168
	global_store_dword v[10:11], v4, off
	v_mov_b32_e32 v7, v149
	s_waitcnt lgkmcnt(0)
	v_mul_f32_e32 v4, v149, v9
	v_pk_fma_f32 v[4:5], v[6:7], v[8:9], v[4:5] op_sel_hi:[1,1,0]
	v_pk_mul_f32 v[2:3], v[2:3], v[8:9]
	s_nop 0
	v_cvt_pk_bf16_f32 v5, v4, v2
	ds_read_b64 v[6:7], v125 offset:7680
	global_store_dword v[10:11], v5, off offset:2048
	v_mov_b32_e32 v5, v150
	s_waitcnt lgkmcnt(0)
	v_mul_f32_e32 v8, v150, v7
	v_pk_fma_f32 v[4:5], v[4:5], v[6:7], v[8:9] op_sel_hi:[1,1,0]
	v_pk_mul_f32 v[2:3], v[2:3], v[6:7]
	v_add_co_u32_e32 v8, vcc, s1, v88
	v_cvt_pk_bf16_f32 v5, v4, v2
	ds_read_b64 v[6:7], v125 offset:8192
	s_nop 0
	v_addc_co_u32_e32 v9, vcc, 0, v89, vcc
	global_store_dword v[8:9], v5, off offset:-4096
	v_mov_b32_e32 v5, v151
	s_waitcnt lgkmcnt(0)
	v_mul_f32_e32 v10, v151, v7
	v_pk_fma_f32 v[4:5], v[4:5], v[6:7], v[10:11] op_sel_hi:[1,1,0]
	v_pk_mul_f32 v[2:3], v[2:3], v[6:7]
	v_add_co_u32_e32 v10, vcc, s0, v88
	v_cvt_pk_bf16_f32 v5, v4, v2
	ds_read_b64 v[6:7], v125 offset:8704
	s_nop 0
	v_addc_co_u32_e32 v11, vcc, 0, v89, vcc
	global_store_dword v[10:11], v5, off offset:2048
	v_mov_b32_e32 v5, v152
	s_waitcnt lgkmcnt(0)
	v_mul_f32_e32 v10, v152, v7
	v_pk_fma_f32 v[4:5], v[4:5], v[6:7], v[10:11] op_sel_hi:[1,1,0]
	v_pk_mul_f32 v[2:3], v[2:3], v[6:7]
	v_cvt_pk_bf16_f32 v5, v4, v2
	ds_read_b64 v[6:7], v125 offset:9216
	global_store_dword v[8:9], v5, off
	v_mov_b32_e32 v5, v153
	s_mov_b32 s1, 0x11f0e000
	s_waitcnt lgkmcnt(0)
	v_mul_f32_e32 v10, v153, v7
	v_pk_fma_f32 v[4:5], v[4:5], v[6:7], v[10:11] op_sel_hi:[1,1,0]
	v_pk_mul_f32 v[2:3], v[2:3], v[6:7]
	s_mov_b32 s0, 0x11f0d000
	v_cvt_pk_bf16_f32 v5, v4, v2
	ds_read_b64 v[6:7], v125 offset:9728
	global_store_dword v[8:9], v5, off offset:2048
	v_mov_b32_e32 v5, v154
	s_waitcnt lgkmcnt(0)
	v_mul_f32_e32 v8, v154, v7
	v_pk_fma_f32 v[4:5], v[4:5], v[6:7], v[8:9] op_sel_hi:[1,1,0]
	v_pk_mul_f32 v[2:3], v[2:3], v[6:7]
	v_add_co_u32_e32 v8, vcc, s1, v88
	v_cvt_pk_bf16_f32 v5, v4, v2
	ds_read_b64 v[6:7], v125 offset:10240
	s_nop 0
	v_addc_co_u32_e32 v9, vcc, 0, v89, vcc
	global_store_dword v[8:9], v5, off offset:-4096
	v_mov_b32_e32 v5, v155
	s_waitcnt lgkmcnt(0)
	v_mul_f32_e32 v10, v155, v7
	v_pk_fma_f32 v[4:5], v[4:5], v[6:7], v[10:11] op_sel_hi:[1,1,0]
	v_pk_mul_f32 v[2:3], v[2:3], v[6:7]
	v_add_co_u32_e32 v10, vcc, s0, v88
	v_cvt_pk_bf16_f32 v5, v4, v2
	ds_read_b64 v[6:7], v125 offset:10752
	s_nop 0
	v_addc_co_u32_e32 v11, vcc, 0, v89, vcc
	global_store_dword v[10:11], v5, off offset:2048
	v_mov_b32_e32 v5, v156
	s_waitcnt lgkmcnt(0)
	v_mul_f32_e32 v10, v156, v7
	v_pk_fma_f32 v[4:5], v[4:5], v[6:7], v[10:11] op_sel_hi:[1,1,0]
	v_pk_mul_f32 v[2:3], v[2:3], v[6:7]
	s_mov_b32 s0, 0x11f0f000
	v_cvt_pk_bf16_f32 v5, v4, v2
	ds_read_b64 v[6:7], v125 offset:11264
	global_store_dword v[8:9], v5, off
	v_mov_b32_e32 v5, v157
	v_lshl_add_u64 v[10:11], s[42:43], 0, v[82:83]
	s_waitcnt lgkmcnt(0)
	v_mul_f32_e32 v12, v157, v7
	v_pk_fma_f32 v[4:5], v[4:5], v[6:7], v[12:13] op_sel_hi:[1,1,0]
	v_pk_mul_f32 v[2:3], v[2:3], v[6:7]
	v_add_co_u32_e32 v12, vcc, s0, v88
	v_cvt_pk_bf16_f32 v5, v4, v2
	ds_read_b64 v[6:7], v125 offset:11776
	global_store_dword v[8:9], v5, off offset:2048
	v_mov_b32_e32 v5, v158
	v_addc_co_u32_e32 v13, vcc, 0, v89, vcc
	s_waitcnt lgkmcnt(0)
; #define LAS __attribute__((address_space(3)))
; template <int DIR, int MODE> ...
;     ...
;         const bf16* wr_ = wl + (size_t)((DIR * 8 + w) * 2) * 4096 + (nt * 32 + r32) * 64 + 8 * h;
; #pragma unroll
;         for (int ks = 0; ks < 4; ++ks) {
;             const bf16x8 bR = *(const bf16x8*)(wr_ + 16 * ks), bI = *(const bf16x8*)(wr_ + 4096 + 16 * ks);
;             accR[nt] = MFMA32(af[ks], bR, accR[nt]); accI[nt] = MFMA32(af[ks], bI, accI[nt]); }
;     }
; #pragma unroll
;     for (int nt = 0; nt < 2; ++nt) {
;         const float nba = prm[DIR][nt][0], nbx = prm[DIR][nt][1], k8l = prm[DIR][nt][2];
; #pragma unroll
;         for (int i = 0; i < 16; ++i) {
;             const float d1 = 1.f + __builtin_amdgcn_exp2f(__builtin_fmaf(accR[nt][i], -1.4426950408889634f, nba));
;             const float d2 = 1.f + __builtin_amdgcn_exp2f(__builtin_fmaf(accI[nt][i], -1.4426950408889634f, nbx));
;             const float inv = __builtin_amdgcn_rcpf(d1 * d2), rr = inv * d2, ii = inv * d1;
;             const float av = __builtin_amdgcn_exp2f(k8l * rr);
;             accR[nt][i] = av; accI[nt][i] = __builtin_amdgcn_sqrtf(fmaxf(__builtin_fmaf(-av, av, 1.f), 0.f)) * ii; }
;     }
;     float hc = 0.f, ap = 1.f;
;     if (MODE == 1) hc = ((const float*)(a.ws + WS_CAR))[(size_t)((b * NCH + ch) * 2 + DIR) * LW + c];
; #pragma unroll
;     for (int hh = 0; hh < 2; ++hh) {
;         const int half = DIR == 0 ? hh : 1 - hh;
; #pragma unroll
;         for (int nt = 0; nt < 2; ++nt)
; #pragma unroll
;             for (int i = 0; i < 8; ++i) { const int tt = 8 * (i >> 2) + 4 * h + (i & 3);
;                 f32x2 v; v.x = accR[nt][8 * half + i]; v.y = accI[nt][8 * half + i];
;                 *(LAS f32x2*)(au + (tt * 64 + nt * 32 + r32) * 2) = v; }
;         LDS_WAVE_SYNC();
; #pragma unroll
;         for (int s = 0; s < 16; ++s) {
;             const int tt = DIR == 0 ? s : 15 - s, t = half * 16 + tt;
;             const f32x2 v = *(const LAS f32x2*)(au + (tt * 64 + lane) * 2);
;             hc = v.x * hc + v.y * xcr[t];
;             if (MODE == 0) { ap *= v.x;
;                 ((unsigned*)(a.ws + WS_HP))[((size_t)DIR * T + (size_t)b * SEQ + ch * 32 + t) * LW + c] = pg8::cvt_pk_bf16(hc, ap); }
;             if (MODE == 1) { if (DIR == 0) hf[t] = hc; else hf[t] = gl[t] * (hf[t] + hc); }
;         }
;         LDS_WAVE_SYNC();
;     }
	v_mul_f32_e32 v8, v158, v7
	v_pk_fma_f32 v[4:5], v[4:5], v[6:7], v[8:9] op_sel_hi:[1,1,0]
	v_pk_mul_f32 v[2:3], v[2:3], v[6:7]
	s_mov_b32 s0, 0x21000
	v_cvt_pk_bf16_f32 v5, v4, v2
	ds_read_b64 v[6:7], v125 offset:12288
	global_store_dword v[12:13], v5, off
	v_mov_b32_e32 v5, v87
	v_add_co_u32_e32 v98, vcc, s0, v90
	s_waitcnt lgkmcnt(0)
	v_mul_f32_e32 v8, v87, v7
	v_pk_mul_f32 v[2:3], v[2:3], v[6:7]
	v_pk_fma_f32 v[4:5], v[4:5], v[6:7], v[8:9] op_sel_hi:[1,1,0]
	v_addc_co_u32_e32 v99, vcc, 0, v91, vcc
	v_cvt_pk_bf16_f32 v3, v4, v2
	global_store_dword v[12:13], v3, off offset:2048
	v_mov_b32_e32 v3, v4
	s_waitcnt lgkmcnt(0)
	global_store_dwordx2 v[10:11], v[2:3], off
	global_load_dwordx4 v[2:5], v[98:99], off offset:-4096
	v_mul_f32_e32 v6, 0xbfb8aa3b, v86
	s_mov_b32 s0, 0x23000
	v_exp_f32_e32 v84, v6
	v_add_co_u32_e32 v122, vcc, s0, v90
	s_mov_b64 s[0:1], 0x20000
	s_nop 0
	v_addc_co_u32_e32 v123, vcc, 0, v91, vcc
	global_load_dwordx4 v[6:9], v[122:123], off offset:-4096
	global_load_dwordx4 v[106:109], v[98:99], off offset:96
	v_lshl_add_u64 v[26:27], v[90:91], 0, s[0:1]
	s_mov_b32 s0, 0x22000
	v_add_f32_e32 v216, 1.0, v163
	v_add_f32_e32 v217, -1.0, v216
	v_log_f32_e32 v218, v216
	v_rcp_f32_e32 v219, v217
	v_cmp_eq_f32_e32 vcc, 0, v217
	v_mul_f32_e32 v218, v218, v163
	v_mul_f32_e32 v218, 0x3f317218, v218
	v_mul_f32_e32 v218, v218, v219
	v_cndmask_b32_e32 v100, v218, v163, vcc
	v_add_co_u32_e32 v30, vcc, s0, v90
	s_nop 1
	v_addc_co_u32_e32 v31, vcc, 0, v91, vcc
	global_load_dwordx4 v[10:13], v[26:27], off offset:32
	global_load_dwordx4 v[18:21], v[26:27], off offset:64
	global_load_dwordx4 v[14:17], v[30:31], off offset:32
	global_load_dwordx4 v[22:25], v[30:31], off offset:64
	global_load_dwordx4 v[26:29], v[26:27], off offset:96
	global_load_dwordx4 v[30:33], v[30:31], off offset:96
	global_load_dwordx4 v[90:93], v[98:99], off
	global_load_dwordx4 v[94:97], v[122:123], off
	s_waitcnt vmcnt(10)
	v_mfma_f32_32x32x16_bf16 v[34:49], v[70:73], v[2:5], 0
	global_load_dwordx4 v[102:105], v[98:99], off offset:32
	global_load_dwordx4 v[114:117], v[98:99], off offset:64
	global_load_dwordx4 v[110:113], v[122:123], off offset:32
	global_load_dwordx4 v[118:121], v[122:123], off offset:64
	global_load_dwordx4 v[164:167], v[122:123], off offset:96
	s_waitcnt vmcnt(14)
	v_mfma_f32_32x32x16_bf16 v[50:65], v[70:73], v[6:9], 0
	s_waitcnt vmcnt(12)
	v_mfma_f32_32x32x16_bf16 v[34:49], v[66:69], v[10:13], v[34:49]
	s_waitcnt vmcnt(10)
	v_mfma_f32_32x32x16_bf16 v[50:65], v[66:69], v[14:17], v[50:65]
	s_mov_b32 s0, 0x13f0f000
	v_mfma_f32_32x32x16_bf16 v[34:49], v[78:81], v[18:21], v[34:49]
	s_waitcnt vmcnt(9)
	v_mfma_f32_32x32x16_bf16 v[50:65], v[78:81], v[22:25], v[50:65]
	s_nop 0
	s_waitcnt vmcnt(8)
	v_mfma_f32_32x32x16_bf16 v[34:49], v[74:77], v[26:29], v[34:49]
	s_waitcnt vmcnt(7)
	v_mfma_f32_32x32x16_bf16 v[50:65], v[74:77], v[30:33], v[50:65]
	s_waitcnt vmcnt(6)
	v_mfma_f32_32x32x16_bf16 v[2:17], v[70:73], v[90:93], 0
	s_waitcnt vmcnt(5)
	v_mfma_f32_32x32x16_bf16 v[18:33], v[70:73], v[94:97], 0
	v_mul_f32_e32 v86, 0xbfb8aa3b, v159
	s_nop 0
	s_waitcnt vmcnt(4)
	v_mfma_f32_32x32x16_bf16 v[2:17], v[66:69], v[102:105], v[2:17]
	v_add_f32_e32 v216, 1.0, v84
	v_add_f32_e32 v217, -1.0, v216
	v_log_f32_e32 v218, v216
	v_rcp_f32_e32 v219, v217
	v_cmp_eq_f32_e32 vcc, 0, v217
	v_mul_f32_e32 v218, v218, v84
	v_mul_f32_e32 v218, 0x3f317218, v218
	v_mul_f32_e32 v218, v218, v219
	v_cndmask_b32_e32 v98, v218, v84, vcc
	v_mul_f32_e32 v102, 0xbfb8aa3b, v160
	v_add_co_u32_e32 v96, vcc, s0, v88
	s_mov_b32 s0, 0x13f0e000
	s_nop 0
	v_addc_co_u32_e32 v97, vcc, 0, v89, vcc
	s_waitcnt vmcnt(2)
	v_mfma_f32_32x32x16_bf16 v[18:33], v[66:69], v[110:113], v[18:33]
	v_add_co_u32_e32 v94, vcc, s0, v88
	s_mov_b32 s0, 0x13f0d000
	s_nop 0
	v_addc_co_u32_e32 v95, vcc, 0, v89, vcc
	v_add_co_u32_e32 v92, vcc, s0, v88
	v_mfma_f32_32x32x16_bf16 v[2:17], v[78:81], v[114:117], v[2:17]
	s_nop 0
	v_addc_co_u32_e32 v93, vcc, 0, v89, vcc
	s_mov_b32 s0, 0x13f0c000
	v_add_co_u32_e32 v90, vcc, s0, v88
	s_mov_b32 s0, 0x13f0b000
	s_nop 0
	v_addc_co_u32_e32 v91, vcc, 0, v89, vcc
	s_waitcnt vmcnt(1)
	v_mfma_f32_32x32x16_bf16 v[18:33], v[78:81], v[118:121], v[18:33]
	v_mul_f32_e32 v80, 0xbfb8aa3b, v161
	v_mul_f32_e32 v81, 0xbfb8aa3b, v162
	v_fmamk_f32 v34, v34, 0xbfb8aa3b, v80
	v_exp_f32_e32 v78, v34
	v_fmamk_f32 v34, v50, 0xbfb8aa3b, v81
	v_exp_f32_e32 v79, v34
	v_fmamk_f32 v36, v36, 0xbfb8aa3b, v80
	v_exp_f32_e32 v50, v36
	v_fmamk_f32 v36, v52, 0xbfb8aa3b, v81
	v_pk_add_f32 v[78:79], v[78:79], 1.0 op_sel_hi:[1,0]
	v_mfma_f32_32x32x16_bf16 v[2:17], v[74:77], v[106:109], v[2:17]
	v_mul_f32_e32 v34, v78, v79
	v_rcp_f32_e32 v84, v34
	v_fmamk_f32 v34, v35, 0xbfb8aa3b, v80
	v_fmamk_f32 v35, v51, 0xbfb8aa3b, v81
	v_exp_f32_e32 v34, v34
	v_exp_f32_e32 v35, v35
	v_exp_f32_e32 v51, v36
	v_mul_f32_e32 v79, v79, v84
	v_mul_f32_e32 v78, v78, v84
	v_pk_add_f32 v[34:35], v[34:35], 1.0 op_sel_hi:[1,0]
	v_pk_add_f32 v[50:51], v[50:51], 1.0 op_sel_hi:[1,0]
	v_mul_f32_e32 v36, v34, v35
	v_rcp_f32_e32 v36, v36
	v_mul_f32_e32 v52, v50, v51
	v_rcp_f32_e32 v52, v52
	s_waitcnt vmcnt(0)
; template <int DIR, int MODE> ...
;     ...
;     for (int nt = 0; nt < 2; ++nt) {
;         const float nba = prm[DIR][nt][0], nbx = prm[DIR][nt][1], k8l = prm[DIR][nt][2];
; #pragma unroll
;         for (int i = 0; i < 16; ++i) {
;             const float d1 = 1.f + __builtin_amdgcn_exp2f(__builtin_fmaf(accR[nt][i], -1.4426950408889634f, nba));
;             const float d2 = 1.f + __builtin_amdgcn_exp2f(__builtin_fmaf(accI[nt][i], -1.4426950408889634f, nbx));
;             const float inv = __builtin_amdgcn_rcpf(d1 * d2), rr = inv * d2, ii = inv * d1;
;             const float av = __builtin_amdgcn_exp2f(k8l * rr);
;             accR[nt][i] = av; accI[nt][i] = __builtin_amdgcn_sqrtf(fmaxf(__builtin_fmaf(-av, av, 1.f), 0.f)) * ii; }
	v_mfma_f32_32x32x16_bf16 v[18:33], v[74:77], v[164:167], v[18:33]
	v_mul_f32_e32 v84, v35, v36
	v_mul_f32_e32 v99, v34, v36
	v_fmamk_f32 v34, v37, 0xbfb8aa3b, v80
	v_fmamk_f32 v35, v53, 0xbfb8aa3b, v81
	v_exp_f32_e32 v34, v34
	v_exp_f32_e32 v35, v35
	v_fmamk_f32 v36, v38, 0xbfb8aa3b, v80
	v_fmamk_f32 v37, v54, 0xbfb8aa3b, v81
	v_exp_f32_e32 v36, v36
	v_exp_f32_e32 v37, v37
	v_pk_add_f32 v[34:35], v[34:35], 1.0 op_sel_hi:[1,0]
	v_mul_f32_e32 v51, v51, v52
	v_mul_f32_e32 v38, v34, v35
	v_rcp_f32_e32 v38, v38
	v_pk_add_f32 v[36:37], v[36:37], 1.0 op_sel_hi:[1,0]
	v_mul_f32_e32 v50, v50, v52
	v_mul_f32_e32 v53, v36, v37
	v_rcp_f32_e32 v53, v53
	v_mul_f32_e32 v52, v35, v38
	v_mul_f32_e32 v54, v34, v38
	v_fmamk_f32 v34, v39, 0xbfb8aa3b, v80
	v_fmamk_f32 v35, v55, 0xbfb8aa3b, v81
	v_exp_f32_e32 v34, v34
	v_exp_f32_e32 v35, v35
	v_mul_f32_e32 v103, v37, v53
	v_fmamk_f32 v37, v40, 0xbfb8aa3b, v80
	v_exp_f32_e32 v38, v37
	v_fmamk_f32 v37, v56, 0xbfb8aa3b, v81
	v_pk_add_f32 v[34:35], v[34:35], 1.0 op_sel_hi:[1,0]
	v_exp_f32_e32 v39, v37
	v_mul_f32_e32 v37, v34, v35
	v_rcp_f32_e32 v37, v37
	v_mul_f32_e32 v53, v36, v53
	v_fmamk_f32 v36, v42, 0xbfb8aa3b, v80
	v_exp_f32_e32 v36, v36
	v_mul_f32_e32 v56, v35, v37
	v_mul_f32_e32 v104, v34, v37
	v_fmamk_f32 v34, v41, 0xbfb8aa3b, v80
	v_fmamk_f32 v35, v57, 0xbfb8aa3b, v81
	v_exp_f32_e32 v34, v34
	v_exp_f32_e32 v35, v35
	v_fmamk_f32 v37, v58, 0xbfb8aa3b, v81
	v_exp_f32_e32 v37, v37
	v_pk_add_f32 v[38:39], v[38:39], 1.0 op_sel_hi:[1,0]
	v_fmamk_f32 v44, v44, 0xbfb8aa3b, v80
	v_mul_f32_e32 v40, v38, v39
	v_rcp_f32_e32 v55, v40
	v_pk_add_f32 v[40:41], v[34:35], 1.0 op_sel_hi:[1,0]
	v_pk_add_f32 v[74:75], v[36:37], 1.0 op_sel_hi:[1,0]
	v_mul_f32_e32 v34, v40, v41
	v_rcp_f32_e32 v35, v34
	v_mul_f32_e32 v34, v74, v75
	v_rcp_f32_e32 v193, v34
	v_mov_b32_e32 v101, v75
	v_mul_f32_e32 v105, v39, v55
	v_mul_f32_e32 v57, v40, v35
	v_pk_mul_f32 v[76:77], v[100:101], v[192:193]
	v_mul_f32_e32 v42, v38, v55
	v_mul_f32_e32 v39, v76, v52
	v_exp_f32_e32 v40, v39
	v_mul_f32_e32 v38, v76, v51
	v_exp_f32_e32 v38, v38
	v_mul_f32_e32 v55, v41, v35
	v_fma_f32 v41, -v40, v40, 1.0
	v_max_f32_e32 v41, 0, v41
	v_mul_f32_e32 v51, v76, v56
	v_fma_f32 v39, -v38, v38, 1.0
	v_sqrt_f32_e32 v41, v41
	v_exp_f32_e32 v52, v51
	v_max_f32_e32 v39, 0, v39
	v_sqrt_f32_e32 v39, v39
	v_mul_f32_e32 v41, v54, v41
	v_fma_f32 v54, -v52, v52, 1.0
	v_max_f32_e32 v56, 0, v54
	v_mul_f32_e32 v54, v76, v105
	v_mul_f32_e32 v39, v50, v39
	v_mul_f32_e32 v50, v76, v103
	v_exp_f32_e32 v54, v54
	v_exp_f32_e32 v50, v50
	v_mul_f32_e32 v55, v76, v55
	v_sqrt_f32_e32 v58, v56
	v_exp_f32_e32 v56, v55
	v_fma_f32 v55, -v54, v54, 1.0
	v_fma_f32 v51, -v50, v50, 1.0
	v_max_f32_e32 v55, 0, v55
	v_max_f32_e32 v51, 0, v51
	v_sqrt_f32_e32 v55, v55
	v_sqrt_f32_e32 v51, v51
	v_fma_f32 v75, -v56, v56, 1.0
	v_max_f32_e32 v75, 0, v75
	v_mul_f32_e32 v55, v42, v55
	v_fmamk_f32 v42, v43, 0xbfb8aa3b, v80
	v_mul_f32_e32 v51, v53, v51
	v_mul_f32_e32 v53, v104, v58
	v_exp_f32_e32 v58, v42
	v_fmamk_f32 v42, v59, 0xbfb8aa3b, v81
	v_mul_f32_e32 v34, v76, v79
	v_sqrt_f32_e32 v75, v75
	v_exp_f32_e32 v59, v42
	v_exp_f32_e32 v34, v34
	v_mul_f32_e32 v42, v76, v77
	v_mul_f32_e32 v35, v76, v84
	v_mul_f32_e32 v57, v57, v75
	v_mul_f32_e32 v43, v74, v193
	v_exp_f32_e32 v42, v42
	v_pk_add_f32 v[74:75], v[58:59], 1.0 op_sel_hi:[1,0]
	v_exp_f32_e32 v36, v35
	v_fma_f32 v35, -v34, v34, 1.0
	v_mul_f32_e32 v58, v74, v75
	v_max_f32_e32 v35, 0, v35
	v_rcp_f32_e32 v59, v58
	v_sqrt_f32_e32 v35, v35
	v_fma_f32 v58, -v42, v42, 1.0
	v_max_f32_e32 v58, 0, v58
	v_sqrt_f32_e32 v77, v58
	v_mul_f32_e32 v58, v75, v59
	v_mul_f32_e32 v35, v78, v35
	v_mul_f32_e32 v58, v76, v58
	v_exp_f32_e32 v78, v44
	v_fmamk_f32 v44, v60, 0xbfb8aa3b, v81
	v_exp_f32_e32 v58, v58
	v_exp_f32_e32 v79, v44
	v_fmamk_f32 v45, v45, 0xbfb8aa3b, v80
	v_mul_f32_e32 v59, v74, v59
	v_fma_f32 v44, -v58, v58, 1.0
	v_pk_add_f32 v[78:79], v[78:79], 1.0 op_sel_hi:[1,0]
	v_max_f32_e32 v44, 0, v44
	v_mul_f32_e32 v60, v78, v79
	v_sqrt_f32_e32 v44, v44
	v_rcp_f32_e32 v75, v60
	v_exp_f32_e32 v60, v45
	v_fmamk_f32 v45, v61, 0xbfb8aa3b, v81
	v_exp_f32_e32 v61, v45
	v_mul_f32_e32 v59, v59, v44
	v_mul_f32_e32 v44, v79, v75
	v_mul_f32_e32 v44, v76, v44
	v_mul_f32_e32 v45, v78, v75
	v_exp_f32_e32 v44, v44
	v_pk_add_f32 v[74:75], v[60:61], 1.0 op_sel_hi:[1,0]
	v_fmamk_f32 v46, v46, 0xbfb8aa3b, v80
	v_mul_f32_e32 v60, v74, v75
	v_rcp_f32_e32 v61, v60
	v_fma_f32 v60, -v44, v44, 1.0
	v_max_f32_e32 v60, 0, v60
	v_mul_f32_e32 v43, v43, v77
	v_sqrt_f32_e32 v77, v60
	v_mul_f32_e32 v60, v75, v61
	v_exp_f32_e32 v78, v46
	v_fmamk_f32 v46, v62, 0xbfb8aa3b, v81
	v_mul_f32_e32 v60, v76, v60
	v_exp_f32_e32 v79, v46
	v_exp_f32_e32 v60, v60
	v_fmamk_f32 v47, v47, 0xbfb8aa3b, v80
	v_mul_f32_e32 v61, v74, v61
	v_pk_add_f32 v[78:79], v[78:79], 1.0 op_sel_hi:[1,0]
	v_fma_f32 v46, -v60, v60, 1.0
	v_mul_f32_e32 v62, v78, v79
	v_max_f32_e32 v46, 0, v46
	v_rcp_f32_e32 v75, v62
	v_exp_f32_e32 v62, v47
	v_fmamk_f32 v47, v63, 0xbfb8aa3b, v81
	v_sqrt_f32_e32 v46, v46
	v_exp_f32_e32 v63, v47
	v_mul_f32_e32 v47, v78, v75
	v_mul_f32_e32 v45, v45, v77
	v_mul_f32_e32 v61, v61, v46
	v_mul_f32_e32 v46, v79, v75
	v_pk_add_f32 v[62:63], v[62:63], 1.0 op_sel_hi:[1,0]
	v_mul_f32_e32 v46, v76, v46
	v_mul_f32_e32 v74, v62, v63
	v_exp_f32_e32 v46, v46
	v_rcp_f32_e32 v75, v74
	v_fmamk_f32 v48, v48, 0xbfb8aa3b, v80
	v_exp_f32_e32 v78, v48
	v_fma_f32 v74, -v46, v46, 1.0
	v_mul_f32_e32 v63, v63, v75
	v_max_f32_e32 v74, 0, v74
	v_mul_f32_e32 v63, v76, v63
	v_sqrt_f32_e32 v77, v74
	v_exp_f32_e32 v74, v63
	v_fmamk_f32 v48, v64, 0xbfb8aa3b, v81
	v_exp_f32_e32 v79, v48
	v_mul_f32_e32 v62, v62, v75
	v_fma_f32 v48, -v74, v74, 1.0
; template <int DIR, int MODE> ...
;     ...
;     for (int nt = 0; nt < 2; ++nt) {
;         const float nba = prm[DIR][nt][0], nbx = prm[DIR][nt][1], k8l = prm[DIR][nt][2];
; #pragma unroll
;         for (int i = 0; i < 16; ++i) {
;             const float d1 = 1.f + __builtin_amdgcn_exp2f(__builtin_fmaf(accR[nt][i], -1.4426950408889634f, nba));
;             const float d2 = 1.f + __builtin_amdgcn_exp2f(__builtin_fmaf(accI[nt][i], -1.4426950408889634f, nbx));
;             const float inv = __builtin_amdgcn_rcpf(d1 * d2), rr = inv * d2, ii = inv * d1;
;             const float av = __builtin_amdgcn_exp2f(k8l * rr);
;             accR[nt][i] = av; accI[nt][i] = __builtin_amdgcn_sqrtf(fmaxf(__builtin_fmaf(-av, av, 1.f), 0.f)) * ii; }
	v_max_f32_e32 v48, 0, v48
	v_sqrt_f32_e32 v48, v48
	v_pk_add_f32 v[78:79], v[78:79], 1.0 op_sel_hi:[1,0]
	v_fmac_f32_e32 v80, 0xbfb8aa3b, v49
	v_mul_f32_e32 v63, v78, v79
	v_fmac_f32_e32 v81, 0xbfb8aa3b, v65
	v_rcp_f32_e32 v63, v63
	v_mul_f32_e32 v75, v62, v48
	v_exp_f32_e32 v48, v80
	v_exp_f32_e32 v49, v81
	v_mul_f32_e32 v62, v79, v63
	v_mul_f32_e32 v62, v76, v62
	v_exp_f32_e32 v62, v62
	v_pk_add_f32 v[48:49], v[48:49], 1.0 op_sel_hi:[1,0]
	v_mul_f32_e32 v63, v78, v63
	v_mul_f32_e32 v64, v48, v49
	v_rcp_f32_e32 v65, v64
	v_fma_f32 v64, -v62, v62, 1.0
	v_max_f32_e32 v64, 0, v64
	v_sqrt_f32_e32 v78, v64
	v_mul_f32_e32 v49, v49, v65
	v_mul_f32_e32 v49, v76, v49
	v_exp_f32_e32 v64, v49
	v_fmamk_f32 v2, v2, 0xbfb8aa3b, v86
	v_exp_f32_e32 v76, v2
	v_fmamk_f32 v2, v18, 0xbfb8aa3b, v102
	v_mul_f32_e32 v47, v47, v77
	v_exp_f32_e32 v77, v2
	v_fma_f32 v2, -v64, v64, 1.0
	v_max_f32_e32 v2, 0, v2
	v_sqrt_f32_e32 v2, v2
	v_pk_add_f32 v[76:77], v[76:77], 1.0 op_sel_hi:[1,0]
	v_fmamk_f32 v4, v4, 0xbfb8aa3b, v86
	v_mul_f32_e32 v18, v76, v77
	v_rcp_f32_e32 v49, v18
	v_mul_f32_e32 v18, v48, v65
	v_mul_f32_e32 v65, v18, v2
	v_fmamk_f32 v2, v3, 0xbfb8aa3b, v86
	v_fmamk_f32 v3, v19, 0xbfb8aa3b, v102
	v_exp_f32_e32 v2, v2
	v_exp_f32_e32 v3, v3
	v_exp_f32_e32 v18, v4
	v_fmamk_f32 v4, v20, 0xbfb8aa3b, v102
	v_exp_f32_e32 v19, v4
	v_pk_add_f32 v[2:3], v[2:3], 1.0 op_sel_hi:[1,0]
	v_mul_f32_e32 v48, v77, v49
	v_mul_f32_e32 v4, v2, v3
	v_rcp_f32_e32 v4, v4
	v_mul_f32_e32 v49, v76, v49
	v_pk_add_f32 v[18:19], v[18:19], 1.0 op_sel_hi:[1,0]
	v_mul_f32_e32 v63, v63, v78
	v_mul_f32_e32 v76, v3, v4
	v_mul_f32_e32 v77, v2, v4
	v_fmamk_f32 v2, v5, 0xbfb8aa3b, v86
	v_fmamk_f32 v3, v21, 0xbfb8aa3b, v102
	v_exp_f32_e32 v2, v2
	v_exp_f32_e32 v3, v3
	v_fmamk_f32 v4, v6, 0xbfb8aa3b, v86
	v_fmamk_f32 v5, v22, 0xbfb8aa3b, v102
	v_mul_f32_e32 v20, v18, v19
	v_exp_f32_e32 v4, v4
	v_exp_f32_e32 v5, v5
	v_pk_add_f32 v[2:3], v[2:3], 1.0 op_sel_hi:[1,0]
	v_rcp_f32_e32 v20, v20
	v_mul_f32_e32 v6, v2, v3
	v_rcp_f32_e32 v6, v6
	v_pk_add_f32 v[4:5], v[4:5], 1.0 op_sel_hi:[1,0]
	v_mul_f32_e32 v78, v19, v20
	v_mul_f32_e32 v19, v4, v5
	v_rcp_f32_e32 v19, v19
	v_mul_f32_e32 v80, v3, v6
	v_mul_f32_e32 v81, v2, v6
	v_fmamk_f32 v2, v7, 0xbfb8aa3b, v86
	v_fmamk_f32 v3, v23, 0xbfb8aa3b, v102
	v_exp_f32_e32 v2, v2
	v_exp_f32_e32 v3, v3
	v_mul_f32_e32 v84, v5, v19
	v_fmamk_f32 v5, v8, 0xbfb8aa3b, v86
	v_exp_f32_e32 v6, v5
	v_fmamk_f32 v5, v24, 0xbfb8aa3b, v102
	v_pk_add_f32 v[2:3], v[2:3], 1.0 op_sel_hi:[1,0]
	v_exp_f32_e32 v7, v5
	v_mul_f32_e32 v5, v2, v3
	v_rcp_f32_e32 v5, v5
	v_fma_f32 v37, -v36, v36, 1.0
	v_pk_add_f32 v[6:7], v[6:7], 1.0 op_sel_hi:[1,0]
	v_max_f32_e32 v37, 0, v37
	v_mul_f32_e32 v8, v6, v7
	v_mul_f32_e32 v101, v3, v5
	v_mul_f32_e32 v103, v2, v5
	v_fmamk_f32 v2, v10, 0xbfb8aa3b, v86
	v_fmamk_f32 v3, v26, 0xbfb8aa3b, v102
	v_rcp_f32_e32 v8, v8
	v_exp_f32_e32 v2, v2
	v_exp_f32_e32 v3, v3
	v_mul_f32_e32 v100, v4, v19
	v_mul_f32_e32 v104, v7, v8
	v_mul_f32_e32 v105, v6, v8
	v_fmamk_f32 v4, v9, 0xbfb8aa3b, v86
	v_pk_add_f32 v[8:9], v[2:3], 1.0 op_sel_hi:[1,0]
	v_sqrt_f32_e32 v37, v37
	v_mul_f32_e32 v2, v8, v9
	v_rcp_f32_e32 v193, v2
	v_fmamk_f32 v2, v25, 0xbfb8aa3b, v102
	v_exp_f32_e32 v4, v4
	v_exp_f32_e32 v5, v2
	v_mul_f32_e32 v37, v99, v37
	v_mov_b32_e32 v99, v9
	v_mul_f32_e32 v79, v18, v20
	v_pk_mul_f32 v[18:19], v[98:99], v[192:193]
	v_pk_add_f32 v[6:7], v[4:5], 1.0 op_sel_hi:[1,0]
	v_mul_f32_e32 v2, v18, v48
	v_exp_f32_e32 v2, v2
	v_mul_f32_e32 v3, v6, v7
	v_rcp_f32_e32 v3, v3
	v_mul_f32_e32 v9, v18, v19
	v_fma_f32 v4, -v2, v2, 1.0
	v_max_f32_e32 v4, 0, v4
	v_sqrt_f32_e32 v5, v4
	v_mul_f32_e32 v4, v18, v76
	v_mul_f32_e32 v76, v6, v3
	v_fmamk_f32 v6, v11, 0xbfb8aa3b, v86
	v_exp_f32_e32 v10, v6
	v_fmamk_f32 v6, v27, 0xbfb8aa3b, v102
	v_exp_f32_e32 v11, v6
	v_mul_f32_e32 v48, v7, v3
	v_exp_f32_e32 v20, v9
	v_mul_f32_e32 v8, v8, v193
	v_pk_add_f32 v[10:11], v[10:11], 1.0 op_sel_hi:[1,0]
	v_add_co_u32_e32 v72, vcc, s0, v88
	v_mul_f32_e32 v7, v10, v11
	v_rcp_f32_e32 v7, v7
	v_addc_co_u32_e32 v73, vcc, 0, v89, vcc
	s_mov_b32 s0, 0x13f0a000
	v_mul_f32_e32 v9, v11, v7
	v_mul_f32_e32 v9, v18, v9
	v_exp_f32_e32 v22, v9
	v_fma_f32 v9, -v20, v20, 1.0
	v_max_f32_e32 v9, 0, v9
	v_sqrt_f32_e32 v9, v9
	v_fma_f32 v11, -v22, v22, 1.0
	v_max_f32_e32 v11, 0, v11
	v_sqrt_f32_e32 v11, v11
	v_mul_f32_e32 v7, v10, v7
	v_mul_f32_e32 v21, v8, v9
	v_add_co_u32_e32 v70, vcc, s0, v88
	v_mul_f32_e32 v23, v7, v11
	v_fmamk_f32 v7, v12, 0xbfb8aa3b, v86
	v_exp_f32_e32 v8, v7
	v_fmamk_f32 v7, v28, 0xbfb8aa3b, v102
	v_exp_f32_e32 v9, v7
	v_fmamk_f32 v7, v13, 0xbfb8aa3b, v86
	v_exp_f32_e32 v10, v7
	v_fmamk_f32 v7, v29, 0xbfb8aa3b, v102
	v_exp_f32_e32 v11, v7
	v_pk_add_f32 v[8:9], v[8:9], 1.0 op_sel_hi:[1,0]
	v_addc_co_u32_e32 v71, vcc, 0, v89, vcc
	v_mul_f32_e32 v7, v8, v9
	v_rcp_f32_e32 v7, v7
	v_pk_add_f32 v[10:11], v[10:11], 1.0 op_sel_hi:[1,0]
	s_mov_b32 s0, 0x13f09000
	v_mul_f32_e32 v12, v10, v11
	v_rcp_f32_e32 v19, v12
	v_mul_f32_e32 v9, v9, v7
	v_mul_f32_e32 v9, v18, v9
	v_exp_f32_e32 v12, v9
	v_mul_f32_e32 v9, v11, v19
	v_mul_f32_e32 v9, v18, v9
	v_exp_f32_e32 v24, v9
	v_fma_f32 v9, -v12, v12, 1.0
	v_max_f32_e32 v9, 0, v9
	v_sqrt_f32_e32 v9, v9
	v_fma_f32 v11, -v24, v24, 1.0
	v_max_f32_e32 v11, 0, v11
	v_sqrt_f32_e32 v11, v11
	v_mul_f32_e32 v7, v8, v7
	v_mul_f32_e32 v13, v7, v9
	v_mul_f32_e32 v7, v10, v19
	v_mul_f32_e32 v25, v7, v11
	v_fmamk_f32 v7, v14, 0xbfb8aa3b, v86
	v_exp_f32_e32 v8, v7
	v_fmamk_f32 v7, v30, 0xbfb8aa3b, v102
	v_exp_f32_e32 v9, v7
	v_fmamk_f32 v7, v15, 0xbfb8aa3b, v86
	v_exp_f32_e32 v10, v7
	v_fmamk_f32 v7, v31, 0xbfb8aa3b, v102
	v_exp_f32_e32 v11, v7
	v_pk_add_f32 v[8:9], v[8:9], 1.0 op_sel_hi:[1,0]
; __device__ __forceinline__ unsigned cvt_pk_bf16(float lo, float hi) { unsigned r; asm volatile("v_cvt_pk_bf16_f32 %0, %1, %2" : "=v"(r) : "v"(lo), "v"(hi)); return r; }
; #define LAS __attribute__((address_space(3)))
; #define LDS_WAVE_SYNC() asm volatile("s_waitcnt lgkmcnt(0)" ::: "memory")
; template <int DIR, int MODE> ...
;     ...
;     for (int nt = 0; nt < 2; ++nt) {
;         const float nba = prm[DIR][nt][0], nbx = prm[DIR][nt][1], k8l = prm[DIR][nt][2];
; #pragma unroll
;         for (int i = 0; i < 16; ++i) {
;             const float d1 = 1.f + __builtin_amdgcn_exp2f(__builtin_fmaf(accR[nt][i], -1.4426950408889634f, nba));
;             const float d2 = 1.f + __builtin_amdgcn_exp2f(__builtin_fmaf(accI[nt][i], -1.4426950408889634f, nbx));
;             const float inv = __builtin_amdgcn_rcpf(d1 * d2), rr = inv * d2, ii = inv * d1;
;             const float av = __builtin_amdgcn_exp2f(k8l * rr);
;             accR[nt][i] = av; accI[nt][i] = __builtin_amdgcn_sqrtf(fmaxf(__builtin_fmaf(-av, av, 1.f), 0.f)) * ii; }
;     }
;     float hc = 0.f, ap = 1.f;
;     if (MODE == 1) hc = ((const float*)(a.ws + WS_CAR))[(size_t)((b * NCH + ch) * 2 + DIR) * LW + c];
; #pragma unroll
;     for (int hh = 0; hh < 2; ++hh) {
;         const int half = DIR == 0 ? hh : 1 - hh;
; #pragma unroll
;         for (int nt = 0; nt < 2; ++nt)
; #pragma unroll
;             for (int i = 0; i < 8; ++i) { const int tt = 8 * (i >> 2) + 4 * h + (i & 3);
;                 f32x2 v; v.x = accR[nt][8 * half + i]; v.y = accI[nt][8 * half + i];
;                 *(LAS f32x2*)(au + (tt * 64 + nt * 32 + r32) * 2) = v; }
;         LDS_WAVE_SYNC();
; #pragma unroll
;         for (int s = 0; s < 16; ++s) {
;             const int tt = DIR == 0 ? s : 15 - s, t = half * 16 + tt;
;             const f32x2 v = *(const LAS f32x2*)(au + (tt * 64 + lane) * 2);
;             hc = v.x * hc + v.y * xcr[t];
;             if (MODE == 0) { ap *= v.x;
;                 ((unsigned*)(a.ws + WS_HP))[((size_t)DIR * T + (size_t)b * SEQ + ch * 32 + t) * LW + c] = pg8::cvt_pk_bf16(hc, ap); }
;             if (MODE == 1) { if (DIR == 0) hf[t] = hc; else hf[t] = gl[t] * (hf[t] + hc); }
;         }
	v_mul_f32_e32 v6, v18, v78
	v_mul_f32_e32 v7, v8, v9
	v_rcp_f32_e32 v7, v7
	v_pk_add_f32 v[10:11], v[10:11], 1.0 op_sel_hi:[1,0]
	v_add_co_u32_e32 v68, vcc, s0, v88
	v_mul_f32_e32 v14, v10, v11
	v_rcp_f32_e32 v19, v14
	v_mul_f32_e32 v9, v9, v7
	v_mul_f32_e32 v9, v18, v9
	v_exp_f32_e32 v14, v9
	v_mul_f32_e32 v9, v11, v19
	v_mul_f32_e32 v9, v18, v9
	v_exp_f32_e32 v26, v9
	v_fma_f32 v9, -v14, v14, 1.0
	v_max_f32_e32 v9, 0, v9
	v_sqrt_f32_e32 v9, v9
	v_fma_f32 v11, -v26, v26, 1.0
	v_max_f32_e32 v11, 0, v11
	v_sqrt_f32_e32 v11, v11
	v_mul_f32_e32 v7, v8, v7
	v_mul_f32_e32 v15, v7, v9
	v_mul_f32_e32 v7, v10, v19
	v_mul_f32_e32 v27, v7, v11
	v_fmamk_f32 v7, v16, 0xbfb8aa3b, v86
	v_exp_f32_e32 v8, v7
	v_fmamk_f32 v7, v32, 0xbfb8aa3b, v102
	v_exp_f32_e32 v9, v7
	v_fmac_f32_e32 v86, 0xbfb8aa3b, v17
	v_fmac_f32_e32 v102, 0xbfb8aa3b, v33
	v_exp_f32_e32 v10, v86
	v_exp_f32_e32 v11, v102
	v_pk_add_f32 v[8:9], v[8:9], 1.0 op_sel_hi:[1,0]
	v_mov_b32_e32 v86, v1
	v_mul_f32_e32 v7, v8, v9
	v_rcp_f32_e32 v7, v7
	v_pk_add_f32 v[10:11], v[10:11], 1.0 op_sel_hi:[1,0]
	v_addc_co_u32_e32 v69, vcc, 0, v89, vcc
	v_mul_f32_e32 v16, v10, v11
	v_rcp_f32_e32 v19, v16
	v_mul_f32_e32 v9, v9, v7
	v_mul_f32_e32 v9, v18, v9
	v_exp_f32_e32 v16, v9
	v_mul_f32_e32 v9, v11, v19
	v_mul_f32_e32 v9, v18, v9
	v_exp_f32_e32 v28, v9
	v_fma_f32 v9, -v16, v16, 1.0
	v_max_f32_e32 v9, 0, v9
	v_sqrt_f32_e32 v9, v9
	v_fma_f32 v11, -v28, v28, 1.0
	v_max_f32_e32 v11, 0, v11
	v_sqrt_f32_e32 v11, v11
	v_mul_f32_e32 v7, v8, v7
	v_mul_f32_e32 v17, v7, v9
	v_mul_f32_e32 v7, v10, v19
	v_mul_f32_e32 v29, v7, v11
	ds_write2_b64 v124, v[42:43], v[20:21] offset0:64 offset1:96
	ds_write2_b64 v124, v[58:59], v[22:23] offset0:128 offset1:160
	ds_write2_b64 v124, v[44:45], v[12:13] offset0:192 offset1:224
	ds_write2_b64 v126, v[60:61], v[24:25] offset1:32
	ds_write2_b64 v127, v[46:47], v[14:15] offset0:64 offset1:96
	ds_write2_b64 v127, v[74:75], v[26:27] offset0:128 offset1:160
	ds_write2_b64 v127, v[62:63], v[16:17] offset0:192 offset1:224
	ds_write2_b64 v128, v[64:65], v[28:29] offset1:32
	s_waitcnt lgkmcnt(0)
	ds_read_b64 v[8:9], v125 offset:12288
	v_mul_f32_e32 v10, v18, v80
	v_exp_f32_e32 v10, v10
	v_mul_f32_e32 v19, v18, v101
	v_exp_f32_e32 v4, v4
	s_waitcnt lgkmcnt(0)
	v_mul_f32_e32 v12, v87, v9
	v_pk_fma_f32 v[12:13], v[86:87], v[8:9], v[12:13] op_sel_hi:[1,1,0]
	v_fma_f32 v17, -v10, v10, 1.0
	v_cvt_pk_bf16_f32 v11, v12, v8
	ds_read_b64 v[14:15], v125 offset:11776
	v_mov_b32_e32 v13, v158
	global_store_dword v[96:97], v11, off offset:2048
	v_exp_f32_e32 v6, v6
	s_mov_b32 s0, 0x13f08000
	s_waitcnt lgkmcnt(0)
	v_mul_f32_e32 v16, v158, v15
	v_pk_fma_f32 v[12:13], v[12:13], v[14:15], v[16:17] op_sel_hi:[1,1,0]
	v_pk_mul_f32 v[8:9], v[8:9], v[14:15]
	v_max_f32_e32 v13, 0, v17
	v_cvt_pk_bf16_f32 v11, v12, v8
	ds_read_b64 v[14:15], v125 offset:11264
	v_sqrt_f32_e32 v17, v13
	v_mov_b32_e32 v13, v157
	global_store_dword v[96:97], v11, off
	v_mul_f32_e32 v3, v49, v5
	s_waitcnt lgkmcnt(0)
	v_mul_f32_e32 v16, v157, v15
	v_pk_fma_f32 v[12:13], v[12:13], v[14:15], v[16:17] op_sel_hi:[1,1,0]
	v_pk_mul_f32 v[8:9], v[8:9], v[14:15]
	v_fma_f32 v5, -v4, v4, 1.0
	v_cvt_pk_bf16_f32 v13, v12, v8
	ds_read_b64 v[14:15], v125 offset:10752
	global_store_dword v[94:95], v13, off offset:2048
	v_mov_b32_e32 v13, v156
	v_fma_f32 v49, -v6, v6, 1.0
	v_mul_f32_e32 v11, v81, v17
	s_waitcnt lgkmcnt(0)
	v_mul_f32_e32 v16, v156, v15
	v_pk_fma_f32 v[12:13], v[12:13], v[14:15], v[16:17] op_sel_hi:[1,1,0]
	v_pk_mul_f32 v[8:9], v[8:9], v[14:15]
	v_mul_f32_e32 v16, v18, v84
	v_cvt_pk_bf16_f32 v13, v12, v8
	ds_read_b64 v[14:15], v125 offset:10240
	global_store_dword v[94:95], v13, off
	v_mov_b32_e32 v13, v155
	v_exp_f32_e32 v16, v16
	v_add_co_u32_e32 v66, vcc, s0, v88
	s_waitcnt lgkmcnt(0)
	v_mul_f32_e32 v20, v155, v15
	v_pk_fma_f32 v[12:13], v[12:13], v[14:15], v[20:21] op_sel_hi:[1,1,0]
	v_pk_mul_f32 v[8:9], v[8:9], v[14:15]
	v_fma_f32 v17, -v16, v16, 1.0
	v_cvt_pk_bf16_f32 v13, v12, v8
	ds_read_b64 v[14:15], v125 offset:9728
	global_store_dword v[92:93], v13, off offset:2048
	v_mov_b32_e32 v13, v154
	v_max_f32_e32 v5, 0, v5
	v_max_f32_e32 v7, 0, v49
	s_waitcnt lgkmcnt(0)
	v_mul_f32_e32 v20, v154, v15
	v_pk_fma_f32 v[12:13], v[12:13], v[14:15], v[20:21] op_sel_hi:[1,1,0]
	v_pk_mul_f32 v[8:9], v[8:9], v[14:15]
	v_exp_f32_e32 v20, v19
	v_cvt_pk_bf16_f32 v13, v12, v8
	ds_read_b64 v[14:15], v125 offset:9216
	global_store_dword v[92:93], v13, off
	v_mov_b32_e32 v13, v153
	v_fma_f32 v19, -v20, v20, 1.0
	v_max_f32_e32 v19, 0, v19
	s_waitcnt lgkmcnt(0)
	v_mul_f32_e32 v22, v153, v15
	v_pk_fma_f32 v[12:13], v[12:13], v[14:15], v[22:23] op_sel_hi:[1,1,0]
	v_pk_mul_f32 v[8:9], v[8:9], v[14:15]
	v_sqrt_f32_e32 v19, v19
	v_cvt_pk_bf16_f32 v13, v12, v8
	ds_read_b64 v[14:15], v125 offset:8704
	global_store_dword v[90:91], v13, off offset:2048
	v_mov_b32_e32 v13, v152
	v_mul_f32_e32 v21, v103, v19
	v_mul_f32_e32 v19, v18, v104
	s_waitcnt lgkmcnt(0)
	v_mul_f32_e32 v22, v152, v15
	v_pk_fma_f32 v[12:13], v[12:13], v[14:15], v[22:23] op_sel_hi:[1,1,0]
	v_pk_mul_f32 v[8:9], v[8:9], v[14:15]
	v_mul_f32_e32 v18, v18, v48
	v_cvt_pk_bf16_f32 v13, v12, v8
	ds_read_b64 v[14:15], v125 offset:8192
	global_store_dword v[90:91], v13, off
	v_mov_b32_e32 v13, v151
	v_exp_f32_e32 v18, v18
	v_max_f32_e32 v17, 0, v17
	s_waitcnt lgkmcnt(0)
	v_mul_f32_e32 v22, v151, v15
	v_pk_fma_f32 v[12:13], v[12:13], v[14:15], v[22:23] op_sel_hi:[1,1,0]
	v_pk_mul_f32 v[8:9], v[8:9], v[14:15]
	v_addc_co_u32_e32 v67, vcc, 0, v89, vcc
	v_cvt_pk_bf16_f32 v13, v12, v8
	ds_read_b64 v[14:15], v125 offset:7680
	global_store_dword v[72:73], v13, off offset:2048
	v_mov_b32_e32 v13, v150
	v_sqrt_f32_e32 v5, v5
	v_sqrt_f32_e32 v7, v7
	s_waitcnt lgkmcnt(0)
; __device__ __forceinline__ unsigned cvt_pk_bf16(float lo, float hi) { unsigned r; asm volatile("v_cvt_pk_bf16_f32 %0, %1, %2" : "=v"(r) : "v"(lo), "v"(hi)); return r; }
; #define LAS __attribute__((address_space(3)))
; #define LDS_WAVE_SYNC() asm volatile("s_waitcnt lgkmcnt(0)" ::: "memory")
; template <int DIR, int MODE> ...
;     ...
;     for (int hh = 0; hh < 2; ++hh) {
;         const int half = DIR == 0 ? hh : 1 - hh;
; #pragma unroll
;         for (int nt = 0; nt < 2; ++nt)
; #pragma unroll
;             for (int i = 0; i < 8; ++i) { const int tt = 8 * (i >> 2) + 4 * h + (i & 3);
;                 f32x2 v; v.x = accR[nt][8 * half + i]; v.y = accI[nt][8 * half + i];
;                 *(LAS f32x2*)(au + (tt * 64 + nt * 32 + r32) * 2) = v; }
;         LDS_WAVE_SYNC();
; #pragma unroll
;         for (int s = 0; s < 16; ++s) {
;             const int tt = DIR == 0 ? s : 15 - s, t = half * 16 + tt;
;             const f32x2 v = *(const LAS f32x2*)(au + (tt * 64 + lane) * 2);
;             hc = v.x * hc + v.y * xcr[t];
;             if (MODE == 0) { ap *= v.x;
;                 ((unsigned*)(a.ws + WS_HP))[((size_t)DIR * T + (size_t)b * SEQ + ch * 32 + t) * LW + c] = pg8::cvt_pk_bf16(hc, ap); }
;             if (MODE == 1) { if (DIR == 0) hf[t] = hc; else hf[t] = gl[t] * (hf[t] + hc); }
;         }
	v_mul_f32_e32 v22, v150, v15
	v_pk_fma_f32 v[12:13], v[12:13], v[14:15], v[22:23] op_sel_hi:[1,1,0]
	v_pk_mul_f32 v[8:9], v[8:9], v[14:15]
	v_fma_f32 v23, -v18, v18, 1.0
	v_cvt_pk_bf16_f32 v13, v12, v8
	ds_read_b64 v[14:15], v125 offset:7168
	global_store_dword v[72:73], v13, off
	v_mov_b32_e32 v13, v149
	v_max_f32_e32 v23, 0, v23
	v_exp_f32_e32 v22, v19
	s_waitcnt lgkmcnt(0)
	v_mul_f32_e32 v24, v149, v15
	v_pk_fma_f32 v[12:13], v[12:13], v[14:15], v[24:25] op_sel_hi:[1,1,0]
	v_pk_mul_f32 v[8:9], v[8:9], v[14:15]
	v_fma_f32 v19, -v22, v22, 1.0
	v_cvt_pk_bf16_f32 v13, v12, v8
	ds_read_b64 v[14:15], v125 offset:6656
	global_store_dword v[70:71], v13, off offset:2048
	v_mov_b32_e32 v13, v148
	v_max_f32_e32 v19, 0, v19
	v_sqrt_f32_e32 v17, v17
	s_waitcnt lgkmcnt(0)
	v_mul_f32_e32 v24, v148, v15
	v_pk_fma_f32 v[12:13], v[12:13], v[14:15], v[24:25] op_sel_hi:[1,1,0]
	v_pk_mul_f32 v[8:9], v[8:9], v[14:15]
	v_sqrt_f32_e32 v19, v19
	v_cvt_pk_bf16_f32 v13, v12, v8
	ds_read_b64 v[14:15], v125 offset:6144
	global_store_dword v[70:71], v13, off
	v_mov_b32_e32 v13, v147
	v_mul_f32_e32 v5, v77, v5
	v_mul_f32_e32 v7, v79, v7
	s_waitcnt lgkmcnt(0)
	v_mul_f32_e32 v24, v147, v15
	v_pk_fma_f32 v[12:13], v[12:13], v[14:15], v[24:25] op_sel_hi:[1,1,0]
	v_pk_mul_f32 v[8:9], v[8:9], v[14:15]
	v_mul_f32_e32 v17, v100, v17
	v_cvt_pk_bf16_f32 v13, v12, v8
	ds_read_b64 v[14:15], v125 offset:5632
	global_store_dword v[68:69], v13, off offset:2048
	v_mov_b32_e32 v13, v146
	s_mov_b32 s0, 0x13f07000
	s_waitcnt lgkmcnt(0)
	v_mul_f32_e32 v24, v146, v15
	v_pk_fma_f32 v[12:13], v[12:13], v[14:15], v[24:25] op_sel_hi:[1,1,0]
	v_pk_mul_f32 v[8:9], v[8:9], v[14:15]
	v_sqrt_f32_e32 v25, v23
	v_cvt_pk_bf16_f32 v13, v12, v8
	ds_read_b64 v[14:15], v125 offset:5120
	global_store_dword v[68:69], v13, off
	v_mov_b32_e32 v13, v145
	v_mul_f32_e32 v23, v105, v19
	v_mul_f32_e32 v19, v76, v25
	s_waitcnt lgkmcnt(0)
	v_mul_f32_e32 v24, v145, v15
	v_pk_fma_f32 v[12:13], v[12:13], v[14:15], v[24:25] op_sel_hi:[1,1,0]
	v_pk_mul_f32 v[8:9], v[8:9], v[14:15]
	s_nop 0
	v_cvt_pk_bf16_f32 v13, v12, v8
	ds_read_b64 v[14:15], v125 offset:4608
	global_store_dword v[66:67], v13, off offset:2048
	v_mov_b32_e32 v13, v144
	s_waitcnt lgkmcnt(0)
	v_mul_f32_e32 v24, v144, v15
	v_pk_fma_f32 v[12:13], v[12:13], v[14:15], v[24:25] op_sel_hi:[1,1,0]
	v_pk_mul_f32 v[8:9], v[8:9], v[14:15]
	s_nop 0
	v_cvt_pk_bf16_f32 v13, v12, v8
	global_store_dword v[66:67], v13, off
	s_waitcnt lgkmcnt(0)
	ds_write2_b64 v124, v[34:35], v[2:3] offset0:64 offset1:96
	ds_write2_b64 v124, v[36:37], v[4:5] offset0:128 offset1:160
	ds_write2_b64 v124, v[38:39], v[6:7] offset0:192 offset1:224
	ds_write2_b64 v126, v[40:41], v[10:11] offset1:32
	ds_write2_b64 v127, v[50:51], v[16:17] offset0:64 offset1:96
	ds_write2_b64 v127, v[52:53], v[20:21] offset0:128 offset1:160
	ds_write2_b64 v127, v[54:55], v[22:23] offset0:192 offset1:224
	ds_write2_b64 v128, v[56:57], v[18:19] offset1:32
	s_waitcnt lgkmcnt(0)
	ds_read_b64 v[2:3], v125 offset:12288
	v_mov_b32_e32 v13, v143
	s_waitcnt lgkmcnt(0)
	v_mul_f32_e32 v4, v143, v3
	v_pk_fma_f32 v[4:5], v[12:13], v[2:3], v[4:5] op_sel_hi:[1,1,0]
	v_pk_mul_f32 v[2:3], v[8:9], v[2:3]
	v_add_co_u32_e32 v8, vcc, s0, v88
	v_cvt_pk_bf16_f32 v5, v4, v2
	ds_read_b64 v[6:7], v125 offset:11776
	s_nop 0
	v_addc_co_u32_e32 v9, vcc, 0, v89, vcc
	global_store_dword v[8:9], v5, off offset:2048
	v_mov_b32_e32 v5, v142
	s_waitcnt lgkmcnt(0)
	v_mul_f32_e32 v10, v142, v7
	v_pk_fma_f32 v[4:5], v[4:5], v[6:7], v[10:11] op_sel_hi:[1,1,0]
	v_pk_mul_f32 v[2:3], v[2:3], v[6:7]
	s_mov_b32 s0, 0x13f06000
	v_cvt_pk_bf16_f32 v5, v4, v2
	ds_read_b64 v[6:7], v125 offset:11264
	global_store_dword v[8:9], v5, off
	v_mov_b32_e32 v5, v141
	v_lshl_add_u64 v[12:13], s[40:41], 0, v[82:83]
	s_waitcnt lgkmcnt(0)
	v_mul_f32_e32 v8, v141, v7
	v_pk_fma_f32 v[4:5], v[4:5], v[6:7], v[8:9] op_sel_hi:[1,1,0]
	v_pk_mul_f32 v[2:3], v[2:3], v[6:7]
	v_add_co_u32_e32 v8, vcc, s0, v88
	v_cvt_pk_bf16_f32 v5, v4, v2
	ds_read_b64 v[6:7], v125 offset:10752
	s_nop 0
	v_addc_co_u32_e32 v9, vcc, 0, v89, vcc
	global_store_dword v[8:9], v5, off offset:2048
	v_mov_b32_e32 v5, v140
	s_waitcnt lgkmcnt(0)
	v_mul_f32_e32 v10, v140, v7
	v_pk_fma_f32 v[4:5], v[4:5], v[6:7], v[10:11] op_sel_hi:[1,1,0]
	v_pk_mul_f32 v[2:3], v[2:3], v[6:7]
	s_mov_b32 s0, 0x13f05000
	v_cvt_pk_bf16_f32 v5, v4, v2
	ds_read_b64 v[6:7], v125 offset:10240
	global_store_dword v[8:9], v5, off
	v_mov_b32_e32 v5, v139
	s_waitcnt lgkmcnt(0)
; __device__ __forceinline__ unsigned cvt_pk_bf16(float lo, float hi) { unsigned r; asm volatile("v_cvt_pk_bf16_f32 %0, %1, %2" : "=v"(r) : "v"(lo), "v"(hi)); return r; }
; #define LAS __attribute__((address_space(3)))
; #define LDS_WAVE_SYNC() asm volatile("s_waitcnt lgkmcnt(0)" ::: "memory")
; template <int DIR, int MODE> ...
;     ...
;     for (int hh = 0; hh < 2; ++hh) {
;         const int half = DIR == 0 ? hh : 1 - hh;
; #pragma unroll
;         for (int nt = 0; nt < 2; ++nt)
; #pragma unroll
;             for (int i = 0; i < 8; ++i) { const int tt = 8 * (i >> 2) + 4 * h + (i & 3);
;                 f32x2 v; v.x = accR[nt][8 * half + i]; v.y = accI[nt][8 * half + i];
;                 *(LAS f32x2*)(au + (tt * 64 + nt * 32 + r32) * 2) = v; }
;         LDS_WAVE_SYNC();
; #pragma unroll
;         for (int s = 0; s < 16; ++s) {
;             const int tt = DIR == 0 ? s : 15 - s, t = half * 16 + tt;
;             const f32x2 v = *(const LAS f32x2*)(au + (tt * 64 + lane) * 2);
;             hc = v.x * hc + v.y * xcr[t];
;             if (MODE == 0) { ap *= v.x;
;                 ((unsigned*)(a.ws + WS_HP))[((size_t)DIR * T + (size_t)b * SEQ + ch * 32 + t) * LW + c] = pg8::cvt_pk_bf16(hc, ap); }
;             if (MODE == 1) { if (DIR == 0) hf[t] = hc; else hf[t] = gl[t] * (hf[t] + hc); }
;         }
;         LDS_WAVE_SYNC();
;     }
;     if (MODE == 0) { f32x2 v; v.x = ap; v.y = hc; ((f32x2*)(a.ws + WS_TOT))[(size_t)((b * NCH + ch) * 2 + DIR) * LW + c] = v; }
	v_mul_f32_e32 v8, v139, v7
	v_pk_fma_f32 v[4:5], v[4:5], v[6:7], v[8:9] op_sel_hi:[1,1,0]
	v_pk_mul_f32 v[2:3], v[2:3], v[6:7]
	v_add_co_u32_e32 v8, vcc, s0, v88
	v_cvt_pk_bf16_f32 v5, v4, v2
	ds_read_b64 v[6:7], v125 offset:9728
	s_nop 0
	v_addc_co_u32_e32 v9, vcc, 0, v89, vcc
	global_store_dword v[8:9], v5, off offset:2048
	v_mov_b32_e32 v5, v138
	s_waitcnt lgkmcnt(0)
	v_mul_f32_e32 v10, v138, v7
	v_pk_fma_f32 v[4:5], v[4:5], v[6:7], v[10:11] op_sel_hi:[1,1,0]
	v_pk_mul_f32 v[2:3], v[2:3], v[6:7]
	s_mov_b32 s0, 0x13f04000
	v_cvt_pk_bf16_f32 v5, v4, v2
	ds_read_b64 v[6:7], v125 offset:9216
	global_store_dword v[8:9], v5, off
	v_mov_b32_e32 v5, v137
	s_waitcnt lgkmcnt(0)
	v_mul_f32_e32 v8, v137, v7
	v_pk_fma_f32 v[4:5], v[4:5], v[6:7], v[8:9] op_sel_hi:[1,1,0]
	v_pk_mul_f32 v[2:3], v[2:3], v[6:7]
	v_add_co_u32_e32 v8, vcc, s0, v88
	v_cvt_pk_bf16_f32 v5, v4, v2
	ds_read_b64 v[6:7], v125 offset:8704
	s_nop 0
	v_addc_co_u32_e32 v9, vcc, 0, v89, vcc
	global_store_dword v[8:9], v5, off offset:2048
	v_mov_b32_e32 v5, v136
	s_waitcnt lgkmcnt(0)
	v_mul_f32_e32 v10, v136, v7
	v_pk_fma_f32 v[4:5], v[4:5], v[6:7], v[10:11] op_sel_hi:[1,1,0]
	v_pk_mul_f32 v[2:3], v[2:3], v[6:7]
	s_mov_b32 s0, 0x13f03000
	v_cvt_pk_bf16_f32 v5, v4, v2
	ds_read_b64 v[6:7], v125 offset:8192
	global_store_dword v[8:9], v5, off
	v_mov_b32_e32 v5, v135
	s_waitcnt lgkmcnt(0)
	v_mul_f32_e32 v8, v135, v7
	v_pk_fma_f32 v[4:5], v[4:5], v[6:7], v[8:9] op_sel_hi:[1,1,0]
	v_pk_mul_f32 v[2:3], v[2:3], v[6:7]
	v_add_co_u32_e32 v8, vcc, s0, v88
	v_cvt_pk_bf16_f32 v5, v4, v2
	ds_read_b64 v[6:7], v125 offset:7680
	s_nop 0
	v_addc_co_u32_e32 v9, vcc, 0, v89, vcc
	global_store_dword v[8:9], v5, off offset:2048
	v_mov_b32_e32 v5, v134
	s_waitcnt lgkmcnt(0)
	v_mul_f32_e32 v10, v134, v7
	v_pk_fma_f32 v[4:5], v[4:5], v[6:7], v[10:11] op_sel_hi:[1,1,0]
	v_pk_mul_f32 v[2:3], v[2:3], v[6:7]
	s_mov_b32 s0, 0x13f02000
	v_cvt_pk_bf16_f32 v5, v4, v2
	ds_read_b64 v[6:7], v125 offset:7168
	global_store_dword v[8:9], v5, off
	v_mov_b32_e32 v5, v133
	s_waitcnt lgkmcnt(0)
	v_mul_f32_e32 v8, v133, v7
	v_pk_fma_f32 v[4:5], v[4:5], v[6:7], v[8:9] op_sel_hi:[1,1,0]
	v_pk_mul_f32 v[2:3], v[2:3], v[6:7]
	v_add_co_u32_e32 v8, vcc, s0, v88
	v_cvt_pk_bf16_f32 v5, v4, v2
	ds_read_b64 v[6:7], v125 offset:6656
	s_nop 0
	v_addc_co_u32_e32 v9, vcc, 0, v89, vcc
	global_store_dword v[8:9], v5, off offset:2048
	v_mov_b32_e32 v5, v132
	s_waitcnt lgkmcnt(0)
	v_mul_f32_e32 v10, v132, v7
	v_pk_fma_f32 v[4:5], v[4:5], v[6:7], v[10:11] op_sel_hi:[1,1,0]
	v_pk_mul_f32 v[2:3], v[2:3], v[6:7]
	s_mov_b32 s0, 0x13f01000
	v_cvt_pk_bf16_f32 v5, v4, v2
	ds_read_b64 v[6:7], v125 offset:6144
	global_store_dword v[8:9], v5, off
	v_mov_b32_e32 v5, v131
	v_add_co_u32_e32 v10, vcc, s0, v88
	s_waitcnt lgkmcnt(0)
	v_mul_f32_e32 v8, v131, v7
	v_pk_fma_f32 v[4:5], v[4:5], v[6:7], v[8:9] op_sel_hi:[1,1,0]
	v_pk_mul_f32 v[2:3], v[2:3], v[6:7]
	v_addc_co_u32_e32 v11, vcc, 0, v89, vcc
	v_cvt_pk_bf16_f32 v5, v4, v2
	ds_read_b64 v[6:7], v125 offset:5632
	global_store_dword v[10:11], v5, off offset:2048
	v_mov_b32_e32 v5, v130
	s_mov_b32 s0, 0x13f00000
	v_add_co_u32_e32 v8, vcc, s0, v88
	s_waitcnt lgkmcnt(0)
	v_mul_f32_e32 v14, v130, v7
	v_pk_fma_f32 v[4:5], v[4:5], v[6:7], v[14:15] op_sel_hi:[1,1,0]
	v_pk_mul_f32 v[2:3], v[2:3], v[6:7]
	v_addc_co_u32_e32 v9, vcc, 0, v89, vcc
	v_cvt_pk_bf16_f32 v5, v4, v2
	ds_read_b64 v[6:7], v125 offset:5120
	global_store_dword v[10:11], v5, off
	v_mov_b32_e32 v5, v0
	v_add_co_u32_e32 v12, vcc, 0x11901000, v12
	s_waitcnt lgkmcnt(0)
	v_mul_f32_e32 v0, v0, v7
	v_pk_fma_f32 v[4:5], v[4:5], v[6:7], v[0:1] op_sel_hi:[1,1,0]
	v_pk_mul_f32 v[2:3], v[2:3], v[6:7]
	v_mov_b32_e32 v5, v85
	v_cvt_pk_bf16_f32 v0, v4, v2
	ds_read_b64 v[6:7], v125 offset:4608
	global_store_dword v[8:9], v0, off offset:2048
	v_addc_co_u32_e32 v13, vcc, 0, v13, vcc
	s_mov_b64 s[0:1], 0
	s_waitcnt lgkmcnt(0)
	v_mul_f32_e32 v0, v85, v7
	v_pk_fma_f32 v[4:5], v[4:5], v[6:7], v[0:1] op_sel_hi:[1,1,0]
	v_pk_mul_f32 v[2:3], v[2:3], v[6:7]
	s_nop 0
	v_cvt_pk_bf16_f32 v0, v4, v2
	global_store_dword v[8:9], v0, off
	s_waitcnt lgkmcnt(0)
	v_mov_b32_e32 v3, v4
	global_store_dwordx2 v[12:13], v[2:3], off
